# speedup vs baseline: 1.0151x; 1.0025x over previous
; __device__ __forceinline__ int tidx() { int t = threadIdx.x; asm volatile("" : "+v"(t)); return t; }
; template <int NT, bool LOWREG = false>
; __device__ __forceinline__ void gemm_mainloop(const bh* __restrict__ A, long lda, const bh* __restrict__ B, long ldb, int K,
;                                               char* lds, f32x4 (&acc)[4][NT]) {
;     ...
;   const int tid = tidx(), lane = tid & 63, wid = tid >> 6, wr = wid >> 1, wc = wid & 1, fr = lane & 15, fq = lane >> 4;
;   const int srow = tid >> 3, scol = (tid & 7) * 8;
;   const bh* Ap = A + (long)srow * lda + scol;
;   const bh* Bp = B + (long)srow * ldb + scol;
;   bf16x8 ra[4], rb[NB];
;   const int nk = K >> 6;
; #pragma unroll
;   for (int i = 0; i < 4; ++i) ra[i] = *reinterpret_cast<const bf16x8*>(Ap + (long)(64 * i) * lda);
; #pragma unroll
;   for (int i = 0; i < NB; ++i) rb[i] = *reinterpret_cast<const bf16x8*>(Bp + (long)(64 * i) * ldb);
; #pragma unroll
;   for (int i = 0; i < 4; ++i) *reinterpret_cast<bf16x8*>(lds + (srow + 64 * i) * LROW + scol * 2) = ra[i];
; #pragma unroll
;   for (int i = 0; i < NB; ++i) *reinterpret_cast<bf16x8*>(lds + A_BYTES + (srow + 64 * i) * LROW + scol * 2) = rb[i];
;   __syncthreads();
; #pragma unroll 1
;   for (int kt = 0; kt < nk; ++kt) {
;     const bool more = kt + 1 < nk;
;     if (more) {
; #pragma unroll
;       for (int i = 0; i < 4; ++i) ra[i] = *reinterpret_cast<const bf16x8*>(Ap + (long)(64 * i) * lda + (kt + 1) * 64);
; #pragma unroll
;       for (int i = 0; i < NB; ++i) rb[i] = *reinterpret_cast<const bf16x8*>(Bp + (long)(64 * i) * ldb + (kt + 1) * 64);
;     }
;     ...
;   for (int tile = (t_first >= 0 ? t_first : (int)blockIdx.x); tile < tm_n * tn_n; tile += (t_first >= 0 ? t_stride : (int)gridDim.x)) {
;     const int tn = tile / tm_n, tm = tile - tn * tm_n;
;     f32x4 acc[4][NT];
; #pragma unroll
;     for (int m = 0; m < 4; ++m)
; #pragma unroll
;       for (int n = 0; n < NT; ++n) acc[m][n] = f32x4{0.f, 0.f, 0.f, 0.f};
;     gemm_mainloop<NT>(A + (long)tm * 256 * lda, lda, Bt + (long)tn * BN * ldb, ldb, K, lds, acc);
.LBB0_207:
	s_ashr_i32 s3, s2, 31
	s_lshl_b64 s[10:11], s[2:3], 19
	s_lshr_b32 s3, s3, 26
	s_add_i32 s3, s2, s3
	s_and_b32 s4, s3, 0xffffffc0
	s_sub_i32 s6, s2, s4
	s_ashr_i32 s7, s6, 31
	s_waitcnt vmcnt(9)
	v_mov_b32_e32 v27, v188
	s_ashr_i32 s8, s3, 6
	s_lshl_b64 s[12:13], s[6:7], 19
	s_add_u32 s16, s38, s12
	v_ashrrev_i32_e32 v40, 3, v27
	v_ashrrev_i32_e32 v41, 31, v40
	s_addc_u32 s17, s39, s13
	v_lshlrev_b64 v[42:43], 11, v[40:41]
	v_lshlrev_b32_e32 v2, 4, v27
	v_lshl_add_u64 v[0:1], s[16:17], 0, v[42:43]
	v_and_b32_e32 v176, 0x70, v2
	v_lshl_add_u64 v[0:1], v[0:1], 0, v[176:177]
	s_mov_b32 s3, 0x20000
	v_add_co_u32_e32 v4, vcc, s3, v0
	s_ashr_i32 s9, s8, 31
	s_nop 0
	v_addc_co_u32_e32 v5, vcc, 0, v1, vcc
	s_mov_b32 s3, 0x40000
	s_lshl_b64 s[12:13], s[8:9], 17
	global_load_dwordx4 v[16:19], v[0:1], off
	global_load_dwordx4 v[20:23], v[4:5], off
	v_add_co_u32_e32 v4, vcc, s3, v0
	s_add_u32 s8, s14, s12
	s_nop 0
	v_addc_co_u32_e32 v5, vcc, 0, v1, vcc
	s_mov_b32 s3, 0x60000
	s_addc_u32 s9, s15, s13
	v_add_co_u32_e32 v0, vcc, s3, v0
	v_lshl_add_u64 v[2:3], s[8:9], 0, v[42:43]
	s_nop 0
	v_addc_co_u32_e32 v1, vcc, 0, v1, vcc
	global_load_dwordx4 v[28:31], v[4:5], off
	global_load_dwordx4 v[32:35], v[0:1], off
	v_lshl_add_u64 v[0:1], v[2:3], 0, v[176:177]
	global_load_dwordx4 v[36:39], v[0:1], off
	v_and_b32_e32 v41, 15, v27
	v_and_b32_e32 v58, 48, v27
	v_lshrrev_b32_e32 v27, 1, v27
	s_mov_b32 s5, 0x7ffffc0
	v_mul_lo_u32 v59, v40, s73
	v_and_or_b32 v40, v27, s5, v41
	v_and_or_b32 v27, v27, 32, v41
	v_mul_lo_u32 v60, v40, s73
	v_lshl_add_u64 v[40:41], s[10:11], 0, v[42:43]
	v_lshl_add_u64 v[42:43], s[12:13], 0, v[42:43]
	s_ashr_i32 s5, s4, 31
	v_mul_u32_u24_e32 v61, 0xa0, v27
	v_or_b32_e32 v27, v40, v176
	v_or_b32_e32 v42, v42, v176
	s_lshl_b64 s[10:11], s[4:5], 19
	v_lshl_add_u64 v[52:53], s[0:1], 0, v[42:43]
	v_mov_b32_e32 v42, s11
	v_subrev_co_u32_e32 v40, vcc, s10, v27
	v_mov_b32_e32 v0, 0
	v_add3_u32 v44, 32, v176, v59
	v_add3_u32 v45, 32, v59, v176
	v_subb_co_u32_e32 v41, vcc, v41, v42, vcc
	s_mov_b32 s3, 0
	s_mov_b64 s[8:9], 0
	v_mov_b32_e32 v1, v0
	v_mov_b32_e32 v2, v0
	v_mov_b32_e32 v3, v0
	v_mov_b32_e32 v4, v0
	v_mov_b32_e32 v5, v0
	v_mov_b32_e32 v6, v0
	v_mov_b32_e32 v7, v0
	v_mov_b32_e32 v8, v0
	v_mov_b32_e32 v9, v0
	v_mov_b32_e32 v10, v0
	v_mov_b32_e32 v11, v0
	v_mov_b32_e32 v12, v0
	v_mov_b32_e32 v13, v0
	v_mov_b32_e32 v14, v0
	v_mov_b32_e32 v15, v0
	v_mov_b32_e32 v24, v0
	v_mov_b32_e32 v25, v0
	v_mov_b32_e32 v26, v0
	v_lshl_add_u64 v[54:55], s[28:29], 0, v[40:41]
	v_mov_b32_e32 v27, v0
	v_mov_b32_e32 v40, v0
	v_mov_b32_e32 v41, v0
	v_mov_b32_e32 v42, v0
	v_mov_b32_e32 v43, v0
	v_mov_b32_e32 v46, v0
	v_mov_b32_e32 v47, v0
	s_waitcnt vmcnt(4)
	ds_write_b128 v44, v[16:19]
	s_waitcnt vmcnt(3)
	ds_write_b128 v44, v[20:23] offset:10240
	s_waitcnt vmcnt(2)
	ds_write_b128 v44, v[28:31] offset:20480
	s_waitcnt vmcnt(1)
	ds_write_b128 v44, v[32:35] offset:30720
	s_waitcnt vmcnt(0)
	ds_write_b128 v45, v[36:39] offset:40960
	v_mov_b32_e32 v44, v0
	v_mov_b32_e32 v45, v0
	v_mov_b32_e32 v48, v0
	v_mov_b32_e32 v49, v0
	v_mov_b32_e32 v50, v0
	v_mov_b32_e32 v51, v0
	s_waitcnt vmcnt(2)
	v_lshl_add_u64 v[28:29], v[54:55], 0, s[8:9]
	v_add_co_u32_e32 v16, vcc, 0x5770000, v28
	s_waitcnt vmcnt(0)
	v_lshl_add_u64 v[36:37], v[52:53], 0, s[8:9]
	v_addc_co_u32_e32 v17, vcc, 0, v29, vcc
	v_add_co_u32_e32 v20, vcc, 0x5790000, v28
	s_nop 1
	v_addc_co_u32_e32 v21, vcc, 0, v29, vcc
	v_add_co_u32_e32 v30, vcc, 0x57b0000, v28
	global_load_dwordx4 v[16:19], v[16:17], off offset:128
	s_nop 0
	global_load_dwordx4 v[20:23], v[20:21], off offset:128
	v_addc_co_u32_e32 v31, vcc, 0, v29, vcc
	v_add_co_u32_e32 v32, vcc, 0x57d0000, v28
	s_nop 1
	v_addc_co_u32_e32 v33, vcc, 0, v29, vcc
	global_load_dwordx4 v[28:31], v[30:31], off offset:128
	s_nop 0
	global_load_dwordx4 v[32:35], v[32:33], off offset:128
	s_nop 0
	global_load_dwordx4 v[36:39], v[36:37], off
	s_waitcnt lgkmcnt(0)
	s_barrier
	s_branch .LBB0_209
; template <int NT, bool LOWREG = false>
; __device__ __forceinline__ void gemm_mainloop(const bh* __restrict__ A, long lda, const bh* __restrict__ B, long ldb, int K,
;                                               char* lds, f32x4 (&acc)[4][NT]) {
;     ...
;   for (int kt = 0; kt < nk; ++kt) {
;     const bool more = kt + 1 < nk;
;     if (more) {
; #pragma unroll
;       for (int i = 0; i < 4; ++i) ra[i] = *reinterpret_cast<const bf16x8*>(Ap + (long)(64 * i) * lda + (kt + 1) * 64);
; #pragma unroll
;       for (int i = 0; i < NB; ++i) rb[i] = *reinterpret_cast<const bf16x8*>(Bp + (long)(64 * i) * ldb + (kt + 1) * 64);
;     }
;     const char* sb = lds + (kt & 1) * STAGE;
;     const char* a_base = sb + (wr * 64 + fr) * LROW + fq * 16;
;     const char* b_base = sb + A_BYTES + (wc * (16 * NT) + fr) * LROW + fq * 16;
; #pragma unroll
;     for (int ks = 0; ks < 2; ++ks) {
;       if constexpr (LOWREG) {
;         bf16x8 bfr[NT];
; #pragma unroll
;         for (int n = 0; n < NT; ++n) bfr[n] = *reinterpret_cast<const bf16x8*>(b_base + n * 16 * LROW + ks * 64);
; #pragma unroll
;         for (int mp = 0; mp < 2; ++mp) {
;           bf16x8 af[2];
; #pragma unroll
;           for (int m = 0; m < 2; ++m) af[m] = *reinterpret_cast<const bf16x8*>(a_base + (mp * 2 + m) * 16 * LROW + ks * 64);
;           __builtin_amdgcn_s_setprio(1);
; #pragma unroll
;           for (int m = 0; m < 2; ++m)
; #pragma unroll
;             for (int n = 0; n < NT; ++n) acc[mp * 2 + m][n] = mfma16(af[m], bfr[n], acc[mp * 2 + m][n]);
;           __builtin_amdgcn_s_setprio(0);
;         }
;       } else {
;       bf16x8 af[4], bfr[NT];
; #pragma unroll
;       for (int m = 0; m < 4; ++m) af[m] = *reinterpret_cast<const bf16x8*>(a_base + m * 16 * LROW + ks * 64);
; #pragma unroll
;       for (int n = 0; n < NT; ++n) bfr[n] = *reinterpret_cast<const bf16x8*>(b_base + n * 16 * LROW + ks * 64);
;       __builtin_amdgcn_s_setprio(1);
; #pragma unroll
;       for (int m = 0; m < 4; ++m)
; #pragma unroll
;         for (int n = 0; n < NT; ++n) acc[m][n] = mfma16(af[m], bfr[n], acc[m][n]);
;       __builtin_amdgcn_s_setprio(0);
;       }
;     }
;     if (more) {
;       char* wb = lds + ((kt + 1) & 1) * STAGE;
; #pragma unroll
;       for (int i = 0; i < 4; ++i) *reinterpret_cast<bf16x8*>(wb + (srow + 64 * i) * LROW + scol * 2) = ra[i];
; #pragma unroll
.LBB0_208:
	s_add_u32 s8, s8, 0x80
	s_addc_u32 s9, s9, 0
	s_cmpk_ge_i32 s8, 0x780
	s_cbranch_scc1 .Lmy_t14g_skip_208
	s_waitcnt vmcnt(2)
	v_lshl_add_u64 v[28:29], v[54:55], 0, s[8:9]
	v_add_co_u32_e32 v16, vcc, 0x5770000, v28
	s_waitcnt vmcnt(0)
	v_lshl_add_u64 v[36:37], v[52:53], 0, s[8:9]
	v_addc_co_u32_e32 v17, vcc, 0, v29, vcc
	v_add_co_u32_e32 v20, vcc, 0x5790000, v28
	s_nop 1
	v_addc_co_u32_e32 v21, vcc, 0, v29, vcc
	v_add_co_u32_e32 v30, vcc, 0x57b0000, v28
	global_load_dwordx4 v[16:19], v[16:17], off offset:128
	s_nop 0
	global_load_dwordx4 v[20:23], v[20:21], off offset:128
	v_addc_co_u32_e32 v31, vcc, 0, v29, vcc
	v_add_co_u32_e32 v32, vcc, 0x57d0000, v28
	s_nop 1
	v_addc_co_u32_e32 v33, vcc, 0, v29, vcc
	global_load_dwordx4 v[28:31], v[30:31], off offset:128
	s_nop 0
	global_load_dwordx4 v[32:35], v[32:33], off offset:128
	s_nop 0
	global_load_dwordx4 v[36:39], v[36:37], off
.Lmy_t14g_skip_208:
	s_cmpk_lg_i32 s8, 0x800
	s_mov_b32 s3, s5
	s_waitcnt lgkmcnt(0)
	s_barrier
	s_cbranch_scc0 .LBB0_206
.LBB0_209:
	s_cmpk_lg_i32 s8, 0x780
	s_cselect_b64 s[10:11], -1, 0
	s_cmpk_eq_i32 s8, 0x780
	s_cbranch_scc1 .LBB0_211
.LBB0_211:
	s_add_i32 s5, s3, 1
	s_bitcmp1_b32 s3, 0
	s_cselect_b32 s3, 0xc800, 0
	s_add_i32 s3, s3, 32
	v_add3_u32 v86, s3, v60, v58
	v_add3_u32 v87, s3, v61, v58
	ds_read_b128 v[62:65], v86
	ds_read_b128 v[66:69], v86 offset:2560
	ds_read_b128 v[70:73], v86 offset:5120
	ds_read_b128 v[74:77], v86 offset:7680
	ds_read_b128 v[78:81], v87 offset:40960
	ds_read_b128 v[82:85], v87 offset:43520
	s_setprio 1
	s_waitcnt lgkmcnt(1)
	v_mfma_f32_16x16x32_bf16 v[48:51], v[62:65], v[78:81], v[48:51]
	s_waitcnt lgkmcnt(0)
	v_mfma_f32_16x16x32_bf16 v[44:47], v[62:65], v[82:85], v[44:47]
	v_mfma_f32_16x16x32_bf16 v[40:43], v[66:69], v[78:81], v[40:43]
	v_mfma_f32_16x16x32_bf16 v[24:27], v[66:69], v[82:85], v[24:27]
	v_mfma_f32_16x16x32_bf16 v[12:15], v[70:73], v[78:81], v[12:15]
	v_mfma_f32_16x16x32_bf16 v[8:11], v[70:73], v[82:85], v[8:11]
	v_mfma_f32_16x16x32_bf16 v[4:7], v[74:77], v[78:81], v[4:7]
	v_mfma_f32_16x16x32_bf16 v[0:3], v[74:77], v[82:85], v[0:3]
	s_setprio 0
	ds_read_b128 v[62:65], v86 offset:64
	ds_read_b128 v[66:69], v86 offset:2624
	ds_read_b128 v[70:73], v86 offset:5184
	ds_read_b128 v[74:77], v86 offset:7744
	ds_read_b128 v[78:81], v87 offset:41024
	ds_read_b128 v[82:85], v87 offset:43584
	s_setprio 1
	s_waitcnt lgkmcnt(1)
	v_mfma_f32_16x16x32_bf16 v[48:51], v[62:65], v[78:81], v[48:51]
	s_waitcnt lgkmcnt(0)
	v_mfma_f32_16x16x32_bf16 v[44:47], v[62:65], v[82:85], v[44:47]
	v_mfma_f32_16x16x32_bf16 v[40:43], v[66:69], v[78:81], v[40:43]
	v_mfma_f32_16x16x32_bf16 v[24:27], v[66:69], v[82:85], v[24:27]
	v_mfma_f32_16x16x32_bf16 v[12:15], v[70:73], v[78:81], v[12:15]
	v_mfma_f32_16x16x32_bf16 v[8:11], v[70:73], v[82:85], v[8:11]
	v_mfma_f32_16x16x32_bf16 v[4:7], v[74:77], v[78:81], v[4:7]
	v_mfma_f32_16x16x32_bf16 v[0:3], v[74:77], v[82:85], v[0:3]
	s_setprio 0
	s_andn2_b64 vcc, exec, s[10:11]
	s_cbranch_vccnz .LBB0_208
	s_bitcmp1_b32 s5, 0
	s_cselect_b32 s3, 0xc800, 0
	s_add_i32 s3, s3, 32
	v_add3_u32 v62, s3, v176, v59
	s_waitcnt vmcnt(4)
	ds_write_b128 v62, v[16:19]
	s_waitcnt vmcnt(3)
	ds_write_b128 v62, v[20:23] offset:10240
	s_waitcnt vmcnt(2)
	ds_write_b128 v62, v[28:31] offset:20480
	s_waitcnt vmcnt(1)
	ds_write_b128 v62, v[32:35] offset:30720
	v_add3_u32 v62, s3, v59, v176
	s_waitcnt vmcnt(0)
	ds_write_b128 v62, v[36:39] offset:40960
	s_branch .LBB0_208

; __device__ __forceinline__ int tidx() { int t = threadIdx.x; asm volatile("" : "+v"(t)); return t; }
; template <int NT, bool LOWREG = false>
; __device__ __forceinline__ void gemm_mainloop(const bh* __restrict__ A, long lda, const bh* __restrict__ B, long ldb, int K,
;                                               char* lds, f32x4 (&acc)[4][NT]) {
;     ...
;   const int tid = tidx(), lane = tid & 63, wid = tid >> 6, wr = wid >> 1, wc = wid & 1, fr = lane & 15, fq = lane >> 4;
;   const int srow = tid >> 3, scol = (tid & 7) * 8;
;   const bh* Ap = A + (long)srow * lda + scol;
;   const bh* Bp = B + (long)srow * ldb + scol;
;   bf16x8 ra[4], rb[NB];
;   const int nk = K >> 6;
; #pragma unroll
;   for (int i = 0; i < 4; ++i) ra[i] = *reinterpret_cast<const bf16x8*>(Ap + (long)(64 * i) * lda);
; #pragma unroll
;   for (int i = 0; i < NB; ++i) rb[i] = *reinterpret_cast<const bf16x8*>(Bp + (long)(64 * i) * ldb);
; #pragma unroll
;   for (int i = 0; i < 4; ++i) *reinterpret_cast<bf16x8*>(lds + (srow + 64 * i) * LROW + scol * 2) = ra[i];
; #pragma unroll
;   for (int i = 0; i < NB; ++i) *reinterpret_cast<bf16x8*>(lds + A_BYTES + (srow + 64 * i) * LROW + scol * 2) = rb[i];
;   __syncthreads();
;     ...
;   for (int tile = (t_first >= 0 ? t_first : (int)blockIdx.x); tile < tm_n * tn_n; tile += (t_first >= 0 ? t_stride : (int)gridDim.x)) {
;     const int tn = tile / tm_n, tm = tile - tn * tm_n;
;     f32x4 acc[4][NT];
; #pragma unroll
;     for (int m = 0; m < 4; ++m)
; #pragma unroll
;       for (int n = 0; n < NT; ++n) acc[m][n] = f32x4{0.f, 0.f, 0.f, 0.f};
;     gemm_mainloop<NT>(A + (long)tm * 256 * lda, lda, Bt + (long)tn * BN * ldb, ldb, K, lds, acc);
.LBB0_369:
	s_ashr_i32 s2, s10, 31
	s_lshr_b32 s2, s2, 26
	s_add_i32 s3, s10, s2
	s_and_b32 s14, s3, 0xffffffc0
	s_sub_i32 s11, s10, s14
	s_ashr_i32 s2, s3, 6
	s_mul_i32 s4, s11, 0x220000
	v_readlane_b32 s5, v252, 40
	s_mul_hi_i32 s3, s11, 0x220000
	s_add_u32 s4, s5, s4
	v_readlane_b32 s5, v252, 41
	s_addc_u32 s5, s5, s3
	v_mov_b32_e32 v14, v188
	v_mov_b64_e32 v[0:1], s[4:5]
	v_ashrrev_i32_e32 v10, 3, v14
	v_lshlrev_b32_e32 v2, 4, v14
	v_mad_i64_i32 v[0:1], s[4:5], v10, s90, v[0:1]
	v_and_b32_e32 v176, 0x70, v2
	v_lshl_add_u64 v[0:1], v[0:1], 0, v[176:177]
	v_add_co_u32_e32 v4, vcc, s25, v0
	s_ashr_i32 s3, s2, 31
	s_nop 0
	v_addc_co_u32_e32 v5, vcc, 0, v1, vcc
	s_lshl_b64 s[6:7], s[2:3], 16
	global_load_dwordx4 v[28:31], v[0:1], off
	global_load_dwordx4 v[32:35], v[4:5], off
	v_add_co_u32_e32 v4, vcc, s26, v0
	s_add_u32 s12, s8, s6
	v_ashrrev_i32_e32 v11, 31, v10
	v_addc_co_u32_e32 v5, vcc, 0, v1, vcc
	s_addc_u32 s13, s9, s7
	v_lshlrev_b64 v[12:13], 9, v[10:11]
	v_add_co_u32_e32 v0, vcc, s27, v0
	v_lshl_add_u64 v[2:3], s[12:13], 0, v[12:13]
	s_nop 0
	v_addc_co_u32_e32 v1, vcc, 0, v1, vcc
	global_load_dwordx4 v[40:43], v[4:5], off
	global_load_dwordx4 v[44:47], v[0:1], off
	v_lshl_add_u64 v[0:1], v[2:3], 0, v[176:177]
	v_add_co_u32_e32 v2, vcc, s31, v0
	v_and_b32_e32 v94, 48, v14
	s_nop 0
	v_addc_co_u32_e32 v3, vcc, 0, v1, vcc
	global_load_dwordx4 v[48:51], v[0:1], off
	global_load_dwordx4 v[56:59], v[2:3], off
	v_and_b32_e32 v11, 15, v14
	s_waitcnt vmcnt(16)
	v_lshrrev_b32_e32 v16, 1, v14
	v_and_b32_e32 v17, 0x4f, v14
	v_mad_i64_i32 v[14:15], s[12:13], v10, s90, 0
	s_mov_b32 s12, 0x7ffffc0
	v_mul_lo_u32 v10, v10, s73
	v_and_or_b32 v11, v16, s12, v11
	v_add3_u32 v96, 32, v176, v10
	v_mul_lo_u32 v97, v11, s73
	v_mad_i64_i32 v[10:11], s[12:13], s10, v192, v[14:15]
	s_mul_hi_i32 s12, s14, 0x220000
	s_mul_i32 s14, s14, 0x220000
	v_or_b32_e32 v10, v10, v176
	v_mov_b32_e32 v14, s12
	v_subrev_co_u32_e32 v10, vcc, s14, v10
	v_mov_b32_e32 v0, 0
	s_nop 0
	v_subb_co_u32_e32 v11, vcc, v11, v14, vcc
	v_lshl_add_u64 v[88:89], s[16:17], 0, v[10:11]
	v_lshl_add_u64 v[10:11], s[6:7], 0, v[12:13]
	v_readlane_b32 s6, v253, 55
	v_or_b32_e32 v10, v10, v176
	v_readlane_b32 s7, v253, 56
	s_mov_b32 s3, 0
	s_mov_b64 s[4:5], 0
	v_mov_b32_e32 v1, v0
	v_mov_b32_e32 v2, v0
	v_mov_b32_e32 v3, v0
	v_mov_b32_e32 v4, v0
	v_mov_b32_e32 v5, v0
	v_mov_b32_e32 v6, v0
	v_mov_b32_e32 v7, v0
	v_mov_b32_e32 v8, v0
	v_mov_b32_e32 v9, v0
	v_mul_u32_u24_e32 v95, 0xa0, v17
	v_lshl_add_u64 v[90:91], s[6:7], 0, v[10:11]
	v_mov_b32_e32 v10, v0
	v_mov_b32_e32 v11, v0
	v_mov_b32_e32 v12, v0
	v_mov_b32_e32 v13, v0
	v_mov_b32_e32 v14, v0
	v_mov_b32_e32 v15, v0
	v_mov_b32_e32 v16, v0
	v_mov_b32_e32 v17, v0
	v_mov_b32_e32 v18, v0
	v_mov_b32_e32 v19, v0
	v_mov_b32_e32 v20, v0
	v_mov_b32_e32 v21, v0
	v_mov_b32_e32 v22, v0
	v_mov_b32_e32 v23, v0
	s_waitcnt vmcnt(15)
	v_mov_b32_e32 v24, v0
	v_mov_b32_e32 v25, v0
	v_mov_b32_e32 v26, v0
	v_mov_b32_e32 v27, v0
	s_waitcnt vmcnt(38)
	v_mov_b32_e32 v36, v0
	v_mov_b32_e32 v37, v0
	v_mov_b32_e32 v38, v0
	v_mov_b32_e32 v39, v0
	v_mov_b32_e32 v52, v0
	v_mov_b32_e32 v53, v0
	v_mov_b32_e32 v54, v0
	v_mov_b32_e32 v55, v0
	v_mov_b32_e32 v60, v0
	v_mov_b32_e32 v61, v0
	v_mov_b32_e32 v62, v0
	v_mov_b32_e32 v63, v0
	v_mov_b32_e32 v64, v0
	v_mov_b32_e32 v65, v0
	v_mov_b32_e32 v66, v0
	v_mov_b32_e32 v67, v0
	v_mov_b32_e32 v68, v0
	v_mov_b32_e32 v69, v0
	v_mov_b32_e32 v70, v0
	v_mov_b32_e32 v71, v0
	v_mov_b32_e32 v72, v0
	v_mov_b32_e32 v73, v0
	v_mov_b32_e32 v74, v0
	v_mov_b32_e32 v75, v0
	v_mov_b32_e32 v76, v0
	v_mov_b32_e32 v77, v0
	v_mov_b32_e32 v78, v0
	v_mov_b32_e32 v79, v0
	v_mov_b32_e32 v80, v0
	v_mov_b32_e32 v81, v0
	v_mov_b32_e32 v82, v0
	v_mov_b32_e32 v83, v0
	v_mov_b32_e32 v84, v0
	v_mov_b32_e32 v85, v0
	v_mov_b32_e32 v86, v0
	v_mov_b32_e32 v87, v0
	s_waitcnt vmcnt(5)
	ds_write_b128 v96, v[28:31]
	s_waitcnt vmcnt(4)
	ds_write_b128 v96, v[32:35] offset:10240
	s_waitcnt vmcnt(3)
	ds_write_b128 v96, v[40:43] offset:20480
	s_waitcnt vmcnt(2)
	ds_write_b128 v96, v[44:47] offset:30720
	s_waitcnt vmcnt(1)
	ds_write_b128 v96, v[48:51] offset:40960
	s_waitcnt vmcnt(0)
	ds_write_b128 v96, v[56:59] offset:51200
	s_waitcnt vmcnt(3)
	v_lshl_add_u64 v[40:41], v[88:89], 0, s[4:5]
	v_add_co_u32_e32 v28, vcc, 0x7770000, v40
	s_waitcnt vmcnt(1)
	v_lshl_add_u64 v[48:49], v[90:91], 0, s[4:5]
	v_addc_co_u32_e32 v29, vcc, 0, v41, vcc
	v_add_co_u32_e32 v32, vcc, 0x77f8000, v40
	s_nop 1
	v_addc_co_u32_e32 v33, vcc, 0, v41, vcc
	v_add_co_u32_e32 v42, vcc, 0x7880000, v40
	global_load_dwordx4 v[28:31], v[28:29], off offset:3968
	s_nop 0
	global_load_dwordx4 v[32:35], v[32:33], off offset:3968
	v_addc_co_u32_e32 v43, vcc, 0, v41, vcc
	v_add_co_u32_e32 v44, vcc, 0x7908000, v40
	s_nop 1
	v_addc_co_u32_e32 v45, vcc, 0, v41, vcc
	v_add_co_u32_e32 v50, vcc, 0x16b8000, v48
	global_load_dwordx4 v[40:43], v[42:43], off offset:3968
	s_nop 0
	global_load_dwordx4 v[44:47], v[44:45], off offset:3968
	v_addc_co_u32_e32 v51, vcc, 0, v49, vcc
	s_waitcnt vmcnt(4)
	v_add_co_u32_e32 v56, vcc, 0x16c0000, v48
	s_nop 1
	v_addc_co_u32_e32 v57, vcc, 0, v49, vcc
	global_load_dwordx4 v[48:51], v[50:51], off offset:128
	s_nop 0
	global_load_dwordx4 v[56:59], v[56:57], off offset:128
	s_waitcnt lgkmcnt(0)
	s_barrier
	s_branch .LBB0_371
; template <int NT, bool LOWREG = false>
; __device__ __forceinline__ void gemm_mainloop(const bh* __restrict__ A, long lda, const bh* __restrict__ B, long ldb, int K,
;                                               char* lds, f32x4 (&acc)[4][NT]) {
;     ...
;   for (int kt = 0; kt < nk; ++kt) {
;     const bool more = kt + 1 < nk;
;     if (more) {
; #pragma unroll
;       for (int i = 0; i < 4; ++i) ra[i] = *reinterpret_cast<const bf16x8*>(Ap + (long)(64 * i) * lda + (kt + 1) * 64);
; #pragma unroll
;       for (int i = 0; i < NB; ++i) rb[i] = *reinterpret_cast<const bf16x8*>(Bp + (long)(64 * i) * ldb + (kt + 1) * 64);
;     }
;     const char* sb = lds + (kt & 1) * STAGE;
;     const char* a_base = sb + (wr * 64 + fr) * LROW + fq * 16;
;     const char* b_base = sb + A_BYTES + (wc * (16 * NT) + fr) * LROW + fq * 16;
; #pragma unroll
;     for (int ks = 0; ks < 2; ++ks) {
;       if constexpr (LOWREG) {
;         bf16x8 bfr[NT];
; #pragma unroll
;         for (int n = 0; n < NT; ++n) bfr[n] = *reinterpret_cast<const bf16x8*>(b_base + n * 16 * LROW + ks * 64);
; #pragma unroll
;         for (int mp = 0; mp < 2; ++mp) {
;           bf16x8 af[2];
; #pragma unroll
;           for (int m = 0; m < 2; ++m) af[m] = *reinterpret_cast<const bf16x8*>(a_base + (mp * 2 + m) * 16 * LROW + ks * 64);
;           __builtin_amdgcn_s_setprio(1);
; #pragma unroll
;           for (int m = 0; m < 2; ++m)
; #pragma unroll
;             for (int n = 0; n < NT; ++n) acc[mp * 2 + m][n] = mfma16(af[m], bfr[n], acc[mp * 2 + m][n]);
;           __builtin_amdgcn_s_setprio(0);
;         }
;       } else {
;       bf16x8 af[4], bfr[NT];
; #pragma unroll
;       for (int m = 0; m < 4; ++m) af[m] = *reinterpret_cast<const bf16x8*>(a_base + m * 16 * LROW + ks * 64);
; #pragma unroll
;       for (int n = 0; n < NT; ++n) bfr[n] = *reinterpret_cast<const bf16x8*>(b_base + n * 16 * LROW + ks * 64);
;       __builtin_amdgcn_s_setprio(1);
; #pragma unroll
;       for (int m = 0; m < 4; ++m)
; #pragma unroll
;         for (int n = 0; n < NT; ++n) acc[m][n] = mfma16(af[m], bfr[n], acc[m][n]);
;       __builtin_amdgcn_s_setprio(0);
;       }
;     }
;     if (more) {
;       char* wb = lds + ((kt + 1) & 1) * STAGE;
; #pragma unroll
;       for (int i = 0; i < 4; ++i) *reinterpret_cast<bf16x8*>(wb + (srow + 64 * i) * LROW + scol * 2) = ra[i];
; #pragma unroll
.LBB0_370:
	s_add_u32 s4, s4, 0x80
	s_addc_u32 s5, s5, 0
	s_cmpk_ge_i32 s4, 0x180
	s_cbranch_scc1 .Lmy_t14g_skip_370
	s_waitcnt vmcnt(3)
	v_lshl_add_u64 v[40:41], v[88:89], 0, s[4:5]
	v_add_co_u32_e32 v28, vcc, 0x7770000, v40
	s_waitcnt vmcnt(1)
	v_lshl_add_u64 v[48:49], v[90:91], 0, s[4:5]
	v_addc_co_u32_e32 v29, vcc, 0, v41, vcc
	v_add_co_u32_e32 v32, vcc, 0x77f8000, v40
	s_nop 1
	v_addc_co_u32_e32 v33, vcc, 0, v41, vcc
	v_add_co_u32_e32 v42, vcc, 0x7880000, v40
	global_load_dwordx4 v[28:31], v[28:29], off offset:3968
	s_nop 0
	global_load_dwordx4 v[32:35], v[32:33], off offset:3968
	v_addc_co_u32_e32 v43, vcc, 0, v41, vcc
	v_add_co_u32_e32 v44, vcc, 0x7908000, v40
	s_nop 1
	v_addc_co_u32_e32 v45, vcc, 0, v41, vcc
	v_add_co_u32_e32 v50, vcc, 0x16b8000, v48
	global_load_dwordx4 v[40:43], v[42:43], off offset:3968
	s_nop 0
	global_load_dwordx4 v[44:47], v[44:45], off offset:3968
	v_addc_co_u32_e32 v51, vcc, 0, v49, vcc
	s_waitcnt vmcnt(4)
	v_add_co_u32_e32 v56, vcc, 0x16c0000, v48
	s_nop 1
	v_addc_co_u32_e32 v57, vcc, 0, v49, vcc
	global_load_dwordx4 v[48:51], v[50:51], off offset:128
	s_nop 0
	global_load_dwordx4 v[56:59], v[56:57], off offset:128
.Lmy_t14g_skip_370:
	s_cmpk_lg_i32 s4, 0x200
	s_mov_b32 s3, s12
	s_waitcnt lgkmcnt(0)
	s_barrier
	s_cbranch_scc0 .LBB0_375
.LBB0_371:
	s_cmp_lt_u32 s3, 3
	s_cselect_b64 s[6:7], -1, 0
	s_cmp_gt_u32 s3, 2
	s_cbranch_scc1 .LBB0_373
.LBB0_373:
	s_add_i32 s12, s3, 1
	s_bitcmp1_b32 s3, 0
	s_cselect_b32 s3, 0xf000, 0
	s_add_i32 s3, s3, 32
	v_add3_u32 v130, s3, v97, v94
	v_add3_u32 v131, s3, v95, v94
	ds_read_b128 v[98:101], v130
	ds_read_b128 v[102:105], v130 offset:2560
	ds_read_b128 v[106:109], v130 offset:5120
	ds_read_b128 v[110:113], v130 offset:7680
	ds_read_b128 v[114:117], v131 offset:40960
	ds_read_b128 v[118:121], v131 offset:43520
	ds_read_b128 v[122:125], v131 offset:46080
	ds_read_b128 v[126:129], v131 offset:48640
	s_setprio 1
	s_waitcnt lgkmcnt(3)
	v_mfma_f32_16x16x32_bf16 v[84:87], v[98:101], v[114:117], v[84:87]
	s_waitcnt lgkmcnt(2)
	v_mfma_f32_16x16x32_bf16 v[80:83], v[98:101], v[118:121], v[80:83]
	s_waitcnt lgkmcnt(1)
	v_mfma_f32_16x16x32_bf16 v[76:79], v[98:101], v[122:125], v[76:79]
	s_waitcnt lgkmcnt(0)
	v_mfma_f32_16x16x32_bf16 v[72:75], v[98:101], v[126:129], v[72:75]
	v_mfma_f32_16x16x32_bf16 v[68:71], v[102:105], v[114:117], v[68:71]
	v_mfma_f32_16x16x32_bf16 v[64:67], v[102:105], v[118:121], v[64:67]
	v_mfma_f32_16x16x32_bf16 v[60:63], v[102:105], v[122:125], v[60:63]
	v_mfma_f32_16x16x32_bf16 v[52:55], v[102:105], v[126:129], v[52:55]
	v_mfma_f32_16x16x32_bf16 v[36:39], v[106:109], v[114:117], v[36:39]
	v_mfma_f32_16x16x32_bf16 v[24:27], v[106:109], v[118:121], v[24:27]
	v_mfma_f32_16x16x32_bf16 v[20:23], v[106:109], v[122:125], v[20:23]
	v_mfma_f32_16x16x32_bf16 v[16:19], v[106:109], v[126:129], v[16:19]
	v_mfma_f32_16x16x32_bf16 v[12:15], v[110:113], v[114:117], v[12:15]
	v_mfma_f32_16x16x32_bf16 v[8:11], v[110:113], v[118:121], v[8:11]
	v_mfma_f32_16x16x32_bf16 v[4:7], v[110:113], v[122:125], v[4:7]
	v_mfma_f32_16x16x32_bf16 v[0:3], v[110:113], v[126:129], v[0:3]
	s_setprio 0
	ds_read_b128 v[98:101], v130 offset:64
	ds_read_b128 v[102:105], v130 offset:2624
	ds_read_b128 v[106:109], v130 offset:5184
	ds_read_b128 v[110:113], v130 offset:7744
	ds_read_b128 v[114:117], v131 offset:41024
	ds_read_b128 v[118:121], v131 offset:43584
	ds_read_b128 v[122:125], v131 offset:46144
	ds_read_b128 v[126:129], v131 offset:48704
	s_setprio 1
	s_waitcnt lgkmcnt(3)
	v_mfma_f32_16x16x32_bf16 v[84:87], v[98:101], v[114:117], v[84:87]
	s_waitcnt lgkmcnt(2)
	v_mfma_f32_16x16x32_bf16 v[80:83], v[98:101], v[118:121], v[80:83]
	s_waitcnt lgkmcnt(1)
	v_mfma_f32_16x16x32_bf16 v[76:79], v[98:101], v[122:125], v[76:79]
	s_waitcnt lgkmcnt(0)
	v_mfma_f32_16x16x32_bf16 v[72:75], v[98:101], v[126:129], v[72:75]
	v_mfma_f32_16x16x32_bf16 v[68:71], v[102:105], v[114:117], v[68:71]
	v_mfma_f32_16x16x32_bf16 v[64:67], v[102:105], v[118:121], v[64:67]
	v_mfma_f32_16x16x32_bf16 v[60:63], v[102:105], v[122:125], v[60:63]
	v_mfma_f32_16x16x32_bf16 v[52:55], v[102:105], v[126:129], v[52:55]
	v_mfma_f32_16x16x32_bf16 v[36:39], v[106:109], v[114:117], v[36:39]
	v_mfma_f32_16x16x32_bf16 v[24:27], v[106:109], v[118:121], v[24:27]
	v_mfma_f32_16x16x32_bf16 v[20:23], v[106:109], v[122:125], v[20:23]
	v_mfma_f32_16x16x32_bf16 v[16:19], v[106:109], v[126:129], v[16:19]
	v_mfma_f32_16x16x32_bf16 v[12:15], v[110:113], v[114:117], v[12:15]
	v_mfma_f32_16x16x32_bf16 v[8:11], v[110:113], v[118:121], v[8:11]
	v_mfma_f32_16x16x32_bf16 v[4:7], v[110:113], v[122:125], v[4:7]
	v_mfma_f32_16x16x32_bf16 v[0:3], v[110:113], v[126:129], v[0:3]
	s_setprio 0
	s_andn2_b64 vcc, exec, s[6:7]
	s_cbranch_vccnz .LBB0_370
	s_bitcmp1_b32 s12, 0
	s_cselect_b32 s3, 0xf000, 0
	v_add_u32_e32 v98, s3, v96
	s_waitcnt vmcnt(5)
	ds_write_b128 v98, v[28:31]
	s_waitcnt vmcnt(4)
	ds_write_b128 v98, v[32:35] offset:10240
	s_waitcnt vmcnt(3)
	ds_write_b128 v98, v[40:43] offset:20480
	s_waitcnt vmcnt(2)
	ds_write_b128 v98, v[44:47] offset:30720
	s_waitcnt vmcnt(1)
	ds_write_b128 v98, v[48:51] offset:40960
	s_waitcnt vmcnt(0)
	ds_write_b128 v98, v[56:59] offset:51200
	s_branch .LBB0_370

; __device__ __forceinline__ int tidx() { int t = threadIdx.x; asm volatile("" : "+v"(t)); return t; }
; template <int NT, bool LOWREG = false>
; __device__ __forceinline__ void gemm_mainloop(const bh* __restrict__ A, long lda, const bh* __restrict__ B, long ldb, int K,
;                                               char* lds, f32x4 (&acc)[4][NT]) {
;     ...
;   const int tid = tidx(), lane = tid & 63, wid = tid >> 6, wr = wid >> 1, wc = wid & 1, fr = lane & 15, fq = lane >> 4;
;   const int srow = tid >> 3, scol = (tid & 7) * 8;
;   const bh* Ap = A + (long)srow * lda + scol;
;   const bh* Bp = B + (long)srow * ldb + scol;
;   bf16x8 ra[4], rb[NB];
;   const int nk = K >> 6;
; #pragma unroll
;   for (int i = 0; i < 4; ++i) ra[i] = *reinterpret_cast<const bf16x8*>(Ap + (long)(64 * i) * lda);
; #pragma unroll
;   for (int i = 0; i < NB; ++i) rb[i] = *reinterpret_cast<const bf16x8*>(Bp + (long)(64 * i) * ldb);
; #pragma unroll
;   for (int i = 0; i < 4; ++i) *reinterpret_cast<bf16x8*>(lds + (srow + 64 * i) * LROW + scol * 2) = ra[i];
; #pragma unroll
;   for (int i = 0; i < NB; ++i) *reinterpret_cast<bf16x8*>(lds + A_BYTES + (srow + 64 * i) * LROW + scol * 2) = rb[i];
;   __syncthreads();
; #pragma unroll 1
;   for (int kt = 0; kt < nk; ++kt) {
;     const bool more = kt + 1 < nk;
;     if (more) {
; #pragma unroll
;       for (int i = 0; i < 4; ++i) ra[i] = *reinterpret_cast<const bf16x8*>(Ap + (long)(64 * i) * lda + (kt + 1) * 64);
; #pragma unroll
;       for (int i = 0; i < NB; ++i) rb[i] = *reinterpret_cast<const bf16x8*>(Bp + (long)(64 * i) * ldb + (kt + 1) * 64);
;     }
.LBB0_380:
	s_ashr_i32 s2, s10, 31
	s_lshr_b32 s2, s2, 26
	s_add_i32 s3, s10, s2
	s_and_b32 s14, s3, 0xffffffc0
	s_sub_i32 s11, s10, s14
	s_ashr_i32 s2, s3, 6
	s_mul_i32 s4, s11, 0x220000
	v_readlane_b32 s5, v252, 40
	s_mul_hi_i32 s3, s11, 0x220000
	s_add_u32 s4, s5, s4
	v_readlane_b32 s5, v252, 41
	s_addc_u32 s5, s5, s3
	s_waitcnt vmcnt(4)
	v_mov_b32_e32 v32, v188
	v_mov_b64_e32 v[0:1], s[4:5]
	v_ashrrev_i32_e32 v12, 3, v32
	v_lshlrev_b32_e32 v2, 4, v32
	v_mad_i64_i32 v[0:1], s[4:5], v12, s90, v[0:1]
	v_and_b32_e32 v176, 0x70, v2
	v_lshl_add_u64 v[0:1], v[0:1], 0, v[176:177]
	v_add_co_u32_e32 v4, vcc, s25, v0
	s_ashr_i32 s3, s2, 31
	s_nop 0
	v_addc_co_u32_e32 v5, vcc, 0, v1, vcc
	s_lshl_b64 s[6:7], s[2:3], 16
	global_load_dwordx4 v[16:19], v[0:1], off
	global_load_dwordx4 v[20:23], v[4:5], off
	v_add_co_u32_e32 v4, vcc, s26, v0
	s_add_u32 s12, s8, s6
	v_ashrrev_i32_e32 v13, 31, v12
	v_addc_co_u32_e32 v5, vcc, 0, v1, vcc
	s_addc_u32 s13, s9, s7
	v_lshlrev_b64 v[14:15], 9, v[12:13]
	v_add_co_u32_e32 v0, vcc, s27, v0
	v_lshl_add_u64 v[2:3], s[12:13], 0, v[14:15]
	s_nop 0
	v_addc_co_u32_e32 v1, vcc, 0, v1, vcc
	global_load_dwordx4 v[24:27], v[4:5], off
	global_load_dwordx4 v[28:31], v[0:1], off
	v_lshl_add_u64 v[0:1], v[2:3], 0, v[176:177]
	v_add_co_u32_e32 v2, vcc, s31, v0
	v_and_b32_e32 v93, 48, v32
	s_nop 0
	v_addc_co_u32_e32 v3, vcc, 0, v1, vcc
	global_load_dwordx4 v[36:39], v[0:1], off
	global_load_dwordx4 v[44:47], v[2:3], off
	v_and_b32_e32 v13, 15, v32
	v_lshrrev_b32_e32 v34, 1, v32
	v_and_b32_e32 v35, 0x4f, v32
	v_mad_i64_i32 v[32:33], s[12:13], v12, s90, 0
	v_mul_lo_u32 v12, v12, s73
	s_mov_b32 s12, 0x7ffffc0
	v_and_or_b32 v13, v34, s12, v13
	v_add3_u32 v95, 32, v176, v12
	v_or_b32_e32 v12, v32, v176
	s_mul_hi_i32 s12, s14, 0x220000
	s_mul_i32 s14, s14, 0x220000
	v_mul_lo_u32 v96, v13, s73
	v_mov_b32_e32 v13, s12
	v_subrev_co_u32_e32 v12, vcc, s14, v12
	v_mov_b32_e32 v0, 0
	s_nop 0
	v_subb_co_u32_e32 v13, vcc, v33, v13, vcc
	v_lshl_add_u64 v[88:89], s[0:1], 0, v[12:13]
	v_lshl_add_u64 v[12:13], s[6:7], 0, v[14:15]
	v_readlane_b32 s6, v253, 55
	v_or_b32_e32 v12, v12, v176
	v_readlane_b32 s7, v253, 56
	s_mov_b32 s3, 0
	s_mov_b64 s[4:5], 0
	v_mov_b32_e32 v1, v0
	v_mov_b32_e32 v2, v0
	v_mov_b32_e32 v3, v0
	v_mov_b32_e32 v4, v0
	v_mov_b32_e32 v5, v0
	v_mov_b32_e32 v6, v0
	v_mov_b32_e32 v7, v0
	v_mov_b32_e32 v8, v0
	v_mov_b32_e32 v9, v0
	v_mov_b32_e32 v10, v0
	v_mov_b32_e32 v11, v0
	v_mul_u32_u24_e32 v94, 0xa0, v35
	v_lshl_add_u64 v[90:91], s[6:7], 0, v[12:13]
	v_mov_b32_e32 v12, v0
	v_mov_b32_e32 v13, v0
	v_mov_b32_e32 v14, v0
	v_mov_b32_e32 v15, v0
	v_mov_b32_e32 v32, v0
	v_mov_b32_e32 v33, v0
	v_mov_b32_e32 v34, v0
	v_mov_b32_e32 v35, v0
	s_waitcnt vmcnt(9)
	v_mov_b32_e32 v40, v0
	v_mov_b32_e32 v41, v0
	v_mov_b32_e32 v42, v0
	v_mov_b32_e32 v43, v0
	s_waitcnt vmcnt(7)
	v_mov_b32_e32 v48, v0
	v_mov_b32_e32 v49, v0
	v_mov_b32_e32 v50, v0
	v_mov_b32_e32 v51, v0
	v_mov_b32_e32 v52, v0
	v_mov_b32_e32 v53, v0
	v_mov_b32_e32 v54, v0
	v_mov_b32_e32 v55, v0
	s_waitcnt vmcnt(6)
	v_mov_b32_e32 v56, v0
	v_mov_b32_e32 v57, v0
	v_mov_b32_e32 v58, v0
	v_mov_b32_e32 v59, v0
	v_mov_b32_e32 v60, v0
	v_mov_b32_e32 v61, v0
	v_mov_b32_e32 v62, v0
	v_mov_b32_e32 v63, v0
	v_mov_b32_e32 v64, v0
	v_mov_b32_e32 v65, v0
	v_mov_b32_e32 v66, v0
	v_mov_b32_e32 v67, v0
	v_mov_b32_e32 v68, v0
	v_mov_b32_e32 v69, v0
	v_mov_b32_e32 v70, v0
	v_mov_b32_e32 v71, v0
	v_mov_b32_e32 v72, v0
	v_mov_b32_e32 v73, v0
	v_mov_b32_e32 v74, v0
	v_mov_b32_e32 v75, v0
	v_mov_b32_e32 v76, v0
	v_mov_b32_e32 v77, v0
	v_mov_b32_e32 v78, v0
	v_mov_b32_e32 v79, v0
	v_mov_b32_e32 v80, v0
	v_mov_b32_e32 v81, v0
	v_mov_b32_e32 v82, v0
	v_mov_b32_e32 v83, v0
	v_mov_b32_e32 v84, v0
	v_mov_b32_e32 v85, v0
	v_mov_b32_e32 v86, v0
	v_mov_b32_e32 v87, v0
	s_waitcnt vmcnt(5)
	ds_write_b128 v95, v[16:19]
	s_waitcnt vmcnt(4)
	ds_write_b128 v95, v[20:23] offset:10240
	s_waitcnt vmcnt(3)
	ds_write_b128 v95, v[24:27] offset:20480
	s_waitcnt vmcnt(2)
	ds_write_b128 v95, v[28:31] offset:30720
	s_waitcnt vmcnt(1)
	ds_write_b128 v95, v[36:39] offset:40960
	s_waitcnt vmcnt(0)
	ds_write_b128 v95, v[44:47] offset:51200
	s_waitcnt vmcnt(3)
	v_lshl_add_u64 v[24:25], v[88:89], 0, s[4:5]
	v_add_co_u32_e32 v16, vcc, 0x7770000, v24
	s_waitcnt vmcnt(1)
	v_lshl_add_u64 v[36:37], v[90:91], 0, s[4:5]
	v_addc_co_u32_e32 v17, vcc, 0, v25, vcc
	v_add_co_u32_e32 v20, vcc, 0x77f8000, v24
	s_nop 1
	v_addc_co_u32_e32 v21, vcc, 0, v25, vcc
	v_add_co_u32_e32 v26, vcc, 0x7880000, v24
	global_load_dwordx4 v[16:19], v[16:17], off offset:3968
	s_nop 0
	global_load_dwordx4 v[20:23], v[20:21], off offset:3968
	v_addc_co_u32_e32 v27, vcc, 0, v25, vcc
	v_add_co_u32_e32 v28, vcc, 0x7908000, v24
	s_nop 1
	v_addc_co_u32_e32 v29, vcc, 0, v25, vcc
	v_add_co_u32_e32 v38, vcc, 0x16f8000, v36
	global_load_dwordx4 v[24:27], v[26:27], off offset:3968
	s_nop 0
	global_load_dwordx4 v[28:31], v[28:29], off offset:3968
	v_addc_co_u32_e32 v39, vcc, 0, v37, vcc
	s_waitcnt vmcnt(4)
	v_add_co_u32_e32 v44, vcc, 0x1700000, v36
	s_nop 1
	v_addc_co_u32_e32 v45, vcc, 0, v37, vcc
	global_load_dwordx4 v[36:39], v[38:39], off offset:128
	s_nop 0
	global_load_dwordx4 v[44:47], v[44:45], off offset:128
	s_waitcnt lgkmcnt(0)
	s_barrier
	s_branch .LBB0_382
.LBB0_381:
	s_add_u32 s4, s4, 0x80
	s_addc_u32 s5, s5, 0
	s_cmpk_ge_i32 s4, 0x180
	s_cbranch_scc1 .Lmy_t14g_skip_381
	s_waitcnt vmcnt(3)
	v_lshl_add_u64 v[24:25], v[88:89], 0, s[4:5]
	v_add_co_u32_e32 v16, vcc, 0x7770000, v24
	s_waitcnt vmcnt(1)
	v_lshl_add_u64 v[36:37], v[90:91], 0, s[4:5]
	v_addc_co_u32_e32 v17, vcc, 0, v25, vcc
	v_add_co_u32_e32 v20, vcc, 0x77f8000, v24
	s_nop 1
	v_addc_co_u32_e32 v21, vcc, 0, v25, vcc
	v_add_co_u32_e32 v26, vcc, 0x7880000, v24
	global_load_dwordx4 v[16:19], v[16:17], off offset:3968
	s_nop 0
	global_load_dwordx4 v[20:23], v[20:21], off offset:3968
	v_addc_co_u32_e32 v27, vcc, 0, v25, vcc
	v_add_co_u32_e32 v28, vcc, 0x7908000, v24
	s_nop 1
	v_addc_co_u32_e32 v29, vcc, 0, v25, vcc
	v_add_co_u32_e32 v38, vcc, 0x16f8000, v36
	global_load_dwordx4 v[24:27], v[26:27], off offset:3968
	s_nop 0
	global_load_dwordx4 v[28:31], v[28:29], off offset:3968
	v_addc_co_u32_e32 v39, vcc, 0, v37, vcc
	s_waitcnt vmcnt(4)
	v_add_co_u32_e32 v44, vcc, 0x1700000, v36
	s_nop 1
	v_addc_co_u32_e32 v45, vcc, 0, v37, vcc
	global_load_dwordx4 v[36:39], v[38:39], off offset:128
	s_nop 0
	global_load_dwordx4 v[44:47], v[44:45], off offset:128

; template <int NT, bool LOWREG = false>
; __device__ __forceinline__ void gemm_mainloop(const bh* __restrict__ A, long lda, const bh* __restrict__ B, long ldb, int K,
;                                               char* lds, f32x4 (&acc)[4][NT]) {
;     ...
;   for (int kt = 0; kt < nk; ++kt) {
;     const bool more = kt + 1 < nk;
;     if (more) {
; #pragma unroll
;       for (int i = 0; i < 4; ++i) ra[i] = *reinterpret_cast<const bf16x8*>(Ap + (long)(64 * i) * lda + (kt + 1) * 64);
; #pragma unroll
;       for (int i = 0; i < NB; ++i) rb[i] = *reinterpret_cast<const bf16x8*>(Bp + (long)(64 * i) * ldb + (kt + 1) * 64);
;     }
;     const char* sb = lds + (kt & 1) * STAGE;
;     const char* a_base = sb + (wr * 64 + fr) * LROW + fq * 16;
;     const char* b_base = sb + A_BYTES + (wc * (16 * NT) + fr) * LROW + fq * 16;
; #pragma unroll
;     for (int ks = 0; ks < 2; ++ks) {
;       if constexpr (LOWREG) {
;         bf16x8 bfr[NT];
; #pragma unroll
;         for (int n = 0; n < NT; ++n) bfr[n] = *reinterpret_cast<const bf16x8*>(b_base + n * 16 * LROW + ks * 64);
; #pragma unroll
;         for (int mp = 0; mp < 2; ++mp) {
;           bf16x8 af[2];
; #pragma unroll
;           for (int m = 0; m < 2; ++m) af[m] = *reinterpret_cast<const bf16x8*>(a_base + (mp * 2 + m) * 16 * LROW + ks * 64);
;           __builtin_amdgcn_s_setprio(1);
; #pragma unroll
;           for (int m = 0; m < 2; ++m)
; #pragma unroll
;             for (int n = 0; n < NT; ++n) acc[mp * 2 + m][n] = mfma16(af[m], bfr[n], acc[mp * 2 + m][n]);
;           __builtin_amdgcn_s_setprio(0);
;         }
;       } else {
;       bf16x8 af[4], bfr[NT];
; #pragma unroll
;       for (int m = 0; m < 4; ++m) af[m] = *reinterpret_cast<const bf16x8*>(a_base + m * 16 * LROW + ks * 64);
; #pragma unroll
;       for (int n = 0; n < NT; ++n) bfr[n] = *reinterpret_cast<const bf16x8*>(b_base + n * 16 * LROW + ks * 64);
;       __builtin_amdgcn_s_setprio(1);
; #pragma unroll
;       for (int m = 0; m < 4; ++m)
; #pragma unroll
;         for (int n = 0; n < NT; ++n) acc[m][n] = mfma16(af[m], bfr[n], acc[m][n]);
;       __builtin_amdgcn_s_setprio(0);
;       }
;     }
;     if (more) {
;       char* wb = lds + ((kt + 1) & 1) * STAGE;
; #pragma unroll
;       for (int i = 0; i < 4; ++i) *reinterpret_cast<bf16x8*>(wb + (srow + 64 * i) * LROW + scol * 2) = ra[i];
; #pragma unroll
.LBB0_382:
	s_cmp_lt_u32 s3, 3
	s_cselect_b64 s[6:7], -1, 0
	s_cmp_gt_u32 s3, 2
	s_cbranch_scc1 .LBB0_384
.LBB0_384:
	s_add_i32 s12, s3, 1
	s_bitcmp1_b32 s3, 0
	s_cselect_b32 s3, 0xf000, 0
	s_add_i32 s3, s3, 32
	v_add3_u32 v97, s3, v96, v93
	v_add3_u32 v130, s3, v94, v93
	ds_read_b128 v[98:101], v97
	ds_read_b128 v[102:105], v97 offset:2560
	ds_read_b128 v[106:109], v97 offset:5120
	ds_read_b128 v[110:113], v97 offset:7680
	ds_read_b128 v[114:117], v130 offset:40960
	ds_read_b128 v[118:121], v130 offset:43520
	ds_read_b128 v[122:125], v130 offset:46080
	ds_read_b128 v[126:129], v130 offset:48640
	s_setprio 1
	s_waitcnt lgkmcnt(3)
	v_mfma_f32_16x16x32_bf16 v[84:87], v[98:101], v[114:117], v[84:87]
	s_waitcnt lgkmcnt(2)
	v_mfma_f32_16x16x32_bf16 v[80:83], v[98:101], v[118:121], v[80:83]
	s_waitcnt lgkmcnt(1)
	v_mfma_f32_16x16x32_bf16 v[76:79], v[98:101], v[122:125], v[76:79]
	s_waitcnt lgkmcnt(0)
	v_mfma_f32_16x16x32_bf16 v[72:75], v[98:101], v[126:129], v[72:75]
	v_mfma_f32_16x16x32_bf16 v[68:71], v[102:105], v[114:117], v[68:71]
	v_mfma_f32_16x16x32_bf16 v[64:67], v[102:105], v[118:121], v[64:67]
	v_mfma_f32_16x16x32_bf16 v[60:63], v[102:105], v[122:125], v[60:63]
	v_mfma_f32_16x16x32_bf16 v[56:59], v[102:105], v[126:129], v[56:59]
	v_mfma_f32_16x16x32_bf16 v[52:55], v[106:109], v[114:117], v[52:55]
	v_mfma_f32_16x16x32_bf16 v[48:51], v[106:109], v[118:121], v[48:51]
	v_mfma_f32_16x16x32_bf16 v[40:43], v[106:109], v[122:125], v[40:43]
	v_mfma_f32_16x16x32_bf16 v[32:35], v[106:109], v[126:129], v[32:35]
	v_mfma_f32_16x16x32_bf16 v[12:15], v[110:113], v[114:117], v[12:15]
	v_mfma_f32_16x16x32_bf16 v[8:11], v[110:113], v[118:121], v[8:11]
	v_mfma_f32_16x16x32_bf16 v[4:7], v[110:113], v[122:125], v[4:7]
	v_mfma_f32_16x16x32_bf16 v[0:3], v[110:113], v[126:129], v[0:3]
	s_setprio 0
	ds_read_b128 v[98:101], v97 offset:64
	ds_read_b128 v[102:105], v97 offset:2624
	ds_read_b128 v[106:109], v97 offset:5184
	ds_read_b128 v[110:113], v97 offset:7744
	ds_read_b128 v[114:117], v130 offset:41024
	ds_read_b128 v[118:121], v130 offset:43584
	ds_read_b128 v[122:125], v130 offset:46144
	ds_read_b128 v[126:129], v130 offset:48704
	s_setprio 1
	s_waitcnt lgkmcnt(3)
	v_mfma_f32_16x16x32_bf16 v[84:87], v[98:101], v[114:117], v[84:87]
	s_waitcnt lgkmcnt(2)
	v_mfma_f32_16x16x32_bf16 v[80:83], v[98:101], v[118:121], v[80:83]
	s_waitcnt lgkmcnt(1)
	v_mfma_f32_16x16x32_bf16 v[76:79], v[98:101], v[122:125], v[76:79]
	s_waitcnt lgkmcnt(0)
	v_mfma_f32_16x16x32_bf16 v[72:75], v[98:101], v[126:129], v[72:75]
	v_mfma_f32_16x16x32_bf16 v[68:71], v[102:105], v[114:117], v[68:71]
	v_mfma_f32_16x16x32_bf16 v[64:67], v[102:105], v[118:121], v[64:67]
	v_mfma_f32_16x16x32_bf16 v[60:63], v[102:105], v[122:125], v[60:63]
	v_mfma_f32_16x16x32_bf16 v[56:59], v[102:105], v[126:129], v[56:59]
	v_mfma_f32_16x16x32_bf16 v[52:55], v[106:109], v[114:117], v[52:55]
	v_mfma_f32_16x16x32_bf16 v[48:51], v[106:109], v[118:121], v[48:51]
	v_mfma_f32_16x16x32_bf16 v[40:43], v[106:109], v[122:125], v[40:43]
	v_mfma_f32_16x16x32_bf16 v[32:35], v[106:109], v[126:129], v[32:35]
	v_mfma_f32_16x16x32_bf16 v[12:15], v[110:113], v[114:117], v[12:15]
	v_mfma_f32_16x16x32_bf16 v[8:11], v[110:113], v[118:121], v[8:11]
	v_mfma_f32_16x16x32_bf16 v[4:7], v[110:113], v[122:125], v[4:7]
	v_mfma_f32_16x16x32_bf16 v[0:3], v[110:113], v[126:129], v[0:3]
	s_setprio 0
	s_andn2_b64 vcc, exec, s[6:7]
	s_cbranch_vccnz .LBB0_381
	s_bitcmp1_b32 s12, 0
	s_cselect_b32 s3, 0xf000, 0
	v_add_u32_e32 v97, s3, v95
	s_waitcnt vmcnt(5)
	ds_write_b128 v97, v[16:19]
	s_waitcnt vmcnt(4)
	ds_write_b128 v97, v[20:23] offset:10240
	s_waitcnt vmcnt(3)
	ds_write_b128 v97, v[24:27] offset:20480
	s_waitcnt vmcnt(2)
	ds_write_b128 v97, v[28:31] offset:30720
	s_waitcnt vmcnt(1)
	ds_write_b128 v97, v[36:39] offset:40960
	s_waitcnt vmcnt(0)
	ds_write_b128 v97, v[44:47] offset:51200
	s_branch .LBB0_381

; __device__ __forceinline__ int tidx() { int t = threadIdx.x; asm volatile("" : "+v"(t)); return t; }
; template <int NT, bool LOWREG = false>
; __device__ __forceinline__ void gemm_mainloop(const bh* __restrict__ A, long lda, const bh* __restrict__ B, long ldb, int K,
;                                               char* lds, f32x4 (&acc)[4][NT]) {
;     ...
;   const int tid = tidx(), lane = tid & 63, wid = tid >> 6, wr = wid >> 1, wc = wid & 1, fr = lane & 15, fq = lane >> 4;
;   const int srow = tid >> 3, scol = (tid & 7) * 8;
;   const bh* Ap = A + (long)srow * lda + scol;
;   const bh* Bp = B + (long)srow * ldb + scol;
;   bf16x8 ra[4], rb[NB];
;   const int nk = K >> 6;
; #pragma unroll
;   for (int i = 0; i < 4; ++i) ra[i] = *reinterpret_cast<const bf16x8*>(Ap + (long)(64 * i) * lda);
; #pragma unroll
;   for (int i = 0; i < NB; ++i) rb[i] = *reinterpret_cast<const bf16x8*>(Bp + (long)(64 * i) * ldb);
; #pragma unroll
;   for (int i = 0; i < 4; ++i) *reinterpret_cast<bf16x8*>(lds + (srow + 64 * i) * LROW + scol * 2) = ra[i];
; #pragma unroll
;   for (int i = 0; i < NB; ++i) *reinterpret_cast<bf16x8*>(lds + A_BYTES + (srow + 64 * i) * LROW + scol * 2) = rb[i];
;   __syncthreads();
;     ...
;   for (int tile = (t_first >= 0 ? t_first : (int)blockIdx.x); tile < tm_n * tn_n; tile += (t_first >= 0 ? t_stride : (int)gridDim.x)) {
;     const int tn = tile / tm_n, tm = tile - tn * tm_n;
;     f32x4 acc[4][NT];
; #pragma unroll
;     for (int m = 0; m < 4; ++m)
; #pragma unroll
;       for (int n = 0; n < NT; ++n) acc[m][n] = f32x4{0.f, 0.f, 0.f, 0.f};
;     gemm_mainloop<NT>(A + (long)tm * 256 * lda, lda, Bt + (long)tn * BN * ldb, ldb, K, lds, acc);
.LBB0_451:
	s_abs_i32 s3, s0
	v_readlane_b32 s10, v253, 50
	s_mul_hi_u32 s10, s3, s10
	v_readlane_b32 s15, v253, 36
	s_mul_i32 s11, s10, s15
	s_sub_i32 s3, s3, s11
	s_ashr_i32 s1, s0, 31
	s_add_i32 s11, s10, 1
	s_sub_i32 s14, s3, s15
	s_cmp_ge_u32 s3, s15
	s_cselect_b32 s10, s11, s10
	s_cselect_b32 s3, s14, s3
	s_add_i32 s11, s10, 1
	s_cmp_ge_u32 s3, s15
	s_cselect_b32 s3, s11, s10
	s_xor_b32 s3, s3, s1
	s_sub_i32 s10, s3, s1
	v_readlane_b32 s1, v253, 46
	s_lshl_b32 s16, s10, s1
	s_sub_i32 s14, s0, s16
	s_ashr_i32 s15, s14, 31
	v_mov_b32_e32 v22, v188
	s_lshl_b64 s[18:19], s[14:15], 19
	s_add_u32 s18, s22, s18
	v_ashrrev_i32_e32 v8, 3, v22
	v_ashrrev_i32_e32 v9, 31, v8
	s_addc_u32 s19, s23, s19
	v_lshlrev_b64 v[10:11], 11, v[8:9]
	v_lshlrev_b32_e32 v2, 4, v22
	s_ashr_i32 s11, s10, 31
	v_lshl_add_u64 v[0:1], s[18:19], 0, v[10:11]
	v_and_b32_e32 v176, 0x70, v2
	s_lshl_b64 s[30:31], s[10:11], 18
	s_waitcnt vmcnt(10)
	v_lshl_add_u64 v[16:17], v[0:1], 0, v[176:177]
	s_mov_b32 s3, 0x20000
	s_add_u32 s34, s26, s30
	v_add_co_u32_e32 v4, vcc, s3, v16
	s_addc_u32 s35, s27, s31
	s_nop 0
	v_addc_co_u32_e32 v5, vcc, 0, v17, vcc
	s_mov_b32 s11, 0x40000
	v_lshl_add_u64 v[20:21], s[34:35], 0, v[10:11]
	v_add_co_u32_e32 v12, vcc, s11, v16
	s_mov_b32 s11, 0x60000
	s_nop 0
	v_addc_co_u32_e32 v13, vcc, 0, v17, vcc
	v_lshl_add_u64 v[20:21], v[20:21], 0, v[176:177]
	global_load_dwordx4 v[0:3], v[16:17], off
	global_load_dwordx4 v[24:27], v[20:21], off
	v_add_co_u32_e32 v16, vcc, s11, v16
	global_load_dwordx4 v[4:7], v[4:5], off
	s_nop 0
	v_addc_co_u32_e32 v17, vcc, 0, v17, vcc
	v_add_co_u32_e32 v20, vcc, s3, v20
	global_load_dwordx4 v[12:15], v[12:13], off
	s_nop 0
	v_addc_co_u32_e32 v21, vcc, 0, v21, vcc
	global_load_dwordx4 v[16:19], v[16:17], off
	v_mul_lo_u32 v8, v8, s73
	global_load_dwordx4 v[32:35], v[20:21], off
	v_add3_u32 v94, 32, v176, v8
	v_and_b32_e32 v8, 15, v22
	v_lshrrev_b32_e32 v9, 1, v22
	s_mov_b32 s3, 0x7ffffc0
	v_and_or_b32 v8, v9, s3, v8
	v_mul_lo_u32 v95, v8, s73
	v_and_b32_e32 v8, 0x4f, v22
	v_mul_u32_u24_e32 v96, 0xa0, v8
	v_and_b32_e32 v8, 7, v22
	s_ashr_i32 s17, s16, 31
	v_lshl_or_b32 v10, v8, 4, v10
	s_lshl_b64 s[16:17], s[16:17], 19
	v_subrev_co_u32_e32 v8, vcc, s16, v10
	v_mov_b32_e32 v9, s17
	s_nop 0
	v_subb_co_u32_e32 v9, vcc, v11, v9, vcc
	s_add_u32 s16, s24, s30
	v_lshl_add_u64 v[88:89], s[6:7], 0, v[8:9]
	s_addc_u32 s17, s25, s31
	v_mov_b32_e32 v8, 0
	s_mov_b32 s1, 0
	v_and_b32_e32 v93, 48, v22
	v_lshl_add_u64 v[90:91], s[16:17], 0, v[10:11]
	s_mov_b64 s[16:17], 0
	v_mov_b32_e32 v9, v8
	v_mov_b32_e32 v10, v8
	v_mov_b32_e32 v11, v8
	v_mov_b32_e32 v20, v8
	v_mov_b32_e32 v21, v8
	v_mov_b32_e32 v22, v8
	v_mov_b32_e32 v23, v8
	s_waitcnt vmcnt(11)
	v_mov_b32_e32 v28, v8
	v_mov_b32_e32 v29, v8
	v_mov_b32_e32 v30, v8
	v_mov_b32_e32 v31, v8
	v_mov_b32_e32 v36, v8
	v_mov_b32_e32 v37, v8
	v_mov_b32_e32 v38, v8
	v_mov_b32_e32 v39, v8
	s_waitcnt vmcnt(9)
	v_mov_b32_e32 v40, v8
	v_mov_b32_e32 v41, v8
	v_mov_b32_e32 v42, v8
	v_mov_b32_e32 v43, v8
	s_waitcnt vmcnt(8)
	v_mov_b32_e32 v44, v8
	v_mov_b32_e32 v45, v8
	v_mov_b32_e32 v46, v8
	v_mov_b32_e32 v47, v8
	s_waitcnt vmcnt(7)
	v_mov_b32_e32 v48, v8
	v_mov_b32_e32 v49, v8
	v_mov_b32_e32 v50, v8
	v_mov_b32_e32 v51, v8
	v_mov_b32_e32 v52, v8
	v_mov_b32_e32 v53, v8
	v_mov_b32_e32 v54, v8
	v_mov_b32_e32 v55, v8
	s_waitcnt vmcnt(6)
	v_mov_b32_e32 v56, v8
	v_mov_b32_e32 v57, v8
	v_mov_b32_e32 v58, v8
	v_mov_b32_e32 v59, v8
	v_mov_b32_e32 v60, v8
	v_mov_b32_e32 v61, v8
	v_mov_b32_e32 v62, v8
	v_mov_b32_e32 v63, v8
	v_mov_b32_e32 v64, v8
	v_mov_b32_e32 v65, v8
	v_mov_b32_e32 v66, v8
	v_mov_b32_e32 v67, v8
	v_mov_b32_e32 v68, v8
	v_mov_b32_e32 v69, v8
	v_mov_b32_e32 v70, v8
	v_mov_b32_e32 v71, v8
	v_mov_b32_e32 v72, v8
	v_mov_b32_e32 v73, v8
	v_mov_b32_e32 v74, v8
	v_mov_b32_e32 v75, v8
	v_mov_b32_e32 v76, v8
	v_mov_b32_e32 v77, v8
	v_mov_b32_e32 v78, v8
	v_mov_b32_e32 v79, v8
	v_mov_b32_e32 v80, v8
	v_mov_b32_e32 v81, v8
	v_mov_b32_e32 v82, v8
	v_mov_b32_e32 v83, v8
	v_mov_b32_e32 v84, v8
	v_mov_b32_e32 v85, v8
	v_mov_b32_e32 v86, v8
	v_mov_b32_e32 v87, v8
	s_waitcnt vmcnt(5)
	ds_write_b128 v94, v[0:3]
	s_waitcnt vmcnt(3)
	ds_write_b128 v94, v[4:7] offset:10240
	s_waitcnt vmcnt(2)
	ds_write_b128 v94, v[12:15] offset:20480
	s_waitcnt vmcnt(1)
	ds_write_b128 v94, v[16:19] offset:30720
	ds_write_b128 v94, v[24:27] offset:40960
	s_waitcnt vmcnt(0)
	ds_write_b128 v94, v[32:35] offset:51200
	s_waitcnt vmcnt(3)
	v_lshl_add_u64 v[12:13], v[88:89], 0, s[16:17]
	v_add_co_u32_e32 v0, vcc, 0x1f092000, v12
	s_waitcnt vmcnt(1)
	v_lshl_add_u64 v[24:25], v[90:91], 0, s[16:17]
	v_addc_co_u32_e32 v1, vcc, 0, v13, vcc
	v_add_co_u32_e32 v4, vcc, 0x1f0b2000, v12
	s_nop 1
	v_addc_co_u32_e32 v5, vcc, 0, v13, vcc
	v_add_co_u32_e32 v14, vcc, 0x1f0d2000, v12
	global_load_dwordx4 v[0:3], v[0:1], off offset:128
	s_nop 0
	global_load_dwordx4 v[4:7], v[4:5], off offset:128
	v_addc_co_u32_e32 v15, vcc, 0, v13, vcc
	v_add_co_u32_e32 v16, vcc, 0x1f0f2000, v12
	s_nop 1
	v_addc_co_u32_e32 v17, vcc, 0, v13, vcc
	v_add_co_u32_e32 v26, vcc, 0x1838000, v24
	global_load_dwordx4 v[12:15], v[14:15], off offset:128
	s_nop 0
	global_load_dwordx4 v[16:19], v[16:17], off offset:128
	v_addc_co_u32_e32 v27, vcc, 0, v25, vcc
	s_waitcnt vmcnt(4)
	v_add_co_u32_e32 v32, vcc, 0x1858000, v24
	s_nop 1
	v_addc_co_u32_e32 v33, vcc, 0, v25, vcc
	global_load_dwordx4 v[24:27], v[26:27], off offset:128
	s_nop 0
	global_load_dwordx4 v[32:35], v[32:33], off offset:128
	s_waitcnt lgkmcnt(0)
	s_barrier
	s_branch .LBB0_453
; template <int NT, bool LOWREG = false>
; __device__ __forceinline__ void gemm_mainloop(const bh* __restrict__ A, long lda, const bh* __restrict__ B, long ldb, int K,
;                                               char* lds, f32x4 (&acc)[4][NT]) {
;     ...
;   for (int kt = 0; kt < nk; ++kt) {
;     const bool more = kt + 1 < nk;
;     if (more) {
; #pragma unroll
;       for (int i = 0; i < 4; ++i) ra[i] = *reinterpret_cast<const bf16x8*>(Ap + (long)(64 * i) * lda + (kt + 1) * 64);
; #pragma unroll
;       for (int i = 0; i < NB; ++i) rb[i] = *reinterpret_cast<const bf16x8*>(Bp + (long)(64 * i) * ldb + (kt + 1) * 64);
;     }
;     const char* sb = lds + (kt & 1) * STAGE;
;     const char* a_base = sb + (wr * 64 + fr) * LROW + fq * 16;
;     const char* b_base = sb + A_BYTES + (wc * (16 * NT) + fr) * LROW + fq * 16;
; #pragma unroll
;     for (int ks = 0; ks < 2; ++ks) {
;       if constexpr (LOWREG) {
;         bf16x8 bfr[NT];
; #pragma unroll
;         for (int n = 0; n < NT; ++n) bfr[n] = *reinterpret_cast<const bf16x8*>(b_base + n * 16 * LROW + ks * 64);
; #pragma unroll
;         for (int mp = 0; mp < 2; ++mp) {
;           bf16x8 af[2];
; #pragma unroll
;           for (int m = 0; m < 2; ++m) af[m] = *reinterpret_cast<const bf16x8*>(a_base + (mp * 2 + m) * 16 * LROW + ks * 64);
;           __builtin_amdgcn_s_setprio(1);
; #pragma unroll
;           for (int m = 0; m < 2; ++m)
; #pragma unroll
;             for (int n = 0; n < NT; ++n) acc[mp * 2 + m][n] = mfma16(af[m], bfr[n], acc[mp * 2 + m][n]);
;           __builtin_amdgcn_s_setprio(0);
;         }
;       } else {
;       bf16x8 af[4], bfr[NT];
; #pragma unroll
;       for (int m = 0; m < 4; ++m) af[m] = *reinterpret_cast<const bf16x8*>(a_base + m * 16 * LROW + ks * 64);
; #pragma unroll
;       for (int n = 0; n < NT; ++n) bfr[n] = *reinterpret_cast<const bf16x8*>(b_base + n * 16 * LROW + ks * 64);
;       __builtin_amdgcn_s_setprio(1);
; #pragma unroll
;       for (int m = 0; m < 4; ++m)
; #pragma unroll
;         for (int n = 0; n < NT; ++n) acc[m][n] = mfma16(af[m], bfr[n], acc[m][n]);
;       __builtin_amdgcn_s_setprio(0);
;       }
;     }
;     if (more) {
;       char* wb = lds + ((kt + 1) & 1) * STAGE;
; #pragma unroll
;       for (int i = 0; i < 4; ++i) *reinterpret_cast<bf16x8*>(wb + (srow + 64 * i) * LROW + scol * 2) = ra[i];
; #pragma unroll
.LBB0_452:
	s_add_u32 s16, s16, 0x80
	s_addc_u32 s17, s17, 0
	s_cmpk_ge_i32 s16, 0x780
	s_cbranch_scc1 .Lmy_t14g_skip_452
	s_waitcnt vmcnt(3)
	v_lshl_add_u64 v[12:13], v[88:89], 0, s[16:17]
	v_add_co_u32_e32 v0, vcc, 0x1f092000, v12
	s_waitcnt vmcnt(1)
	v_lshl_add_u64 v[24:25], v[90:91], 0, s[16:17]
	v_addc_co_u32_e32 v1, vcc, 0, v13, vcc
	v_add_co_u32_e32 v4, vcc, 0x1f0b2000, v12
	s_nop 1
	v_addc_co_u32_e32 v5, vcc, 0, v13, vcc
	v_add_co_u32_e32 v14, vcc, 0x1f0d2000, v12
	global_load_dwordx4 v[0:3], v[0:1], off offset:128
	s_nop 0
	global_load_dwordx4 v[4:7], v[4:5], off offset:128
	v_addc_co_u32_e32 v15, vcc, 0, v13, vcc
	v_add_co_u32_e32 v16, vcc, 0x1f0f2000, v12
	s_nop 1
	v_addc_co_u32_e32 v17, vcc, 0, v13, vcc
	v_add_co_u32_e32 v26, vcc, 0x1838000, v24
	global_load_dwordx4 v[12:15], v[14:15], off offset:128
	s_nop 0
	global_load_dwordx4 v[16:19], v[16:17], off offset:128
	v_addc_co_u32_e32 v27, vcc, 0, v25, vcc
	s_waitcnt vmcnt(4)
	v_add_co_u32_e32 v32, vcc, 0x1858000, v24
	s_nop 1
	v_addc_co_u32_e32 v33, vcc, 0, v25, vcc
	global_load_dwordx4 v[24:27], v[26:27], off offset:128
	s_nop 0
	global_load_dwordx4 v[32:35], v[32:33], off offset:128
.Lmy_t14g_skip_452:
	s_cmpk_lg_i32 s16, 0x800
	s_mov_b32 s1, s3
	s_waitcnt lgkmcnt(0)
	s_barrier
	s_cbranch_scc0 .LBB0_450
.LBB0_453:
	s_cmp_lt_u32 s1, 15
	s_cselect_b64 s[18:19], -1, 0
	s_cmp_gt_u32 s1, 14
	s_cbranch_scc1 .LBB0_455
.LBB0_455:
	s_add_i32 s3, s1, 1
	s_bitcmp1_b32 s1, 0
	s_cselect_b32 s1, 0xf000, 0
	s_add_i32 s1, s1, 32
	v_add3_u32 v97, s1, v95, v93
	v_add3_u32 v130, s1, v96, v93
	ds_read_b128 v[98:101], v97
	ds_read_b128 v[102:105], v97 offset:2560
	ds_read_b128 v[106:109], v97 offset:5120
	ds_read_b128 v[110:113], v97 offset:7680
	ds_read_b128 v[114:117], v130 offset:40960
	ds_read_b128 v[118:121], v130 offset:43520
	ds_read_b128 v[122:125], v130 offset:46080
	ds_read_b128 v[126:129], v130 offset:48640
	s_setprio 1
	s_waitcnt lgkmcnt(3)
	v_mfma_f32_16x16x32_bf16 v[84:87], v[98:101], v[114:117], v[84:87]
	s_waitcnt lgkmcnt(2)
	v_mfma_f32_16x16x32_bf16 v[80:83], v[98:101], v[118:121], v[80:83]
	s_waitcnt lgkmcnt(1)
	v_mfma_f32_16x16x32_bf16 v[76:79], v[98:101], v[122:125], v[76:79]
	s_waitcnt lgkmcnt(0)
	v_mfma_f32_16x16x32_bf16 v[72:75], v[98:101], v[126:129], v[72:75]
	v_mfma_f32_16x16x32_bf16 v[68:71], v[102:105], v[114:117], v[68:71]
	v_mfma_f32_16x16x32_bf16 v[64:67], v[102:105], v[118:121], v[64:67]
	v_mfma_f32_16x16x32_bf16 v[60:63], v[102:105], v[122:125], v[60:63]
	v_mfma_f32_16x16x32_bf16 v[56:59], v[102:105], v[126:129], v[56:59]
	v_mfma_f32_16x16x32_bf16 v[52:55], v[106:109], v[114:117], v[52:55]
	v_mfma_f32_16x16x32_bf16 v[48:51], v[106:109], v[118:121], v[48:51]
	v_mfma_f32_16x16x32_bf16 v[44:47], v[106:109], v[122:125], v[44:47]
	v_mfma_f32_16x16x32_bf16 v[40:43], v[106:109], v[126:129], v[40:43]
	v_mfma_f32_16x16x32_bf16 v[36:39], v[110:113], v[114:117], v[36:39]
	v_mfma_f32_16x16x32_bf16 v[28:31], v[110:113], v[118:121], v[28:31]
	v_mfma_f32_16x16x32_bf16 v[20:23], v[110:113], v[122:125], v[20:23]
	v_mfma_f32_16x16x32_bf16 v[8:11], v[110:113], v[126:129], v[8:11]
	s_setprio 0
	ds_read_b128 v[98:101], v97 offset:64
	ds_read_b128 v[102:105], v97 offset:2624
	ds_read_b128 v[106:109], v97 offset:5184
	ds_read_b128 v[110:113], v97 offset:7744
	ds_read_b128 v[114:117], v130 offset:41024
	ds_read_b128 v[118:121], v130 offset:43584
	ds_read_b128 v[122:125], v130 offset:46144
	ds_read_b128 v[126:129], v130 offset:48704
	s_setprio 1
	s_waitcnt lgkmcnt(3)
	v_mfma_f32_16x16x32_bf16 v[84:87], v[98:101], v[114:117], v[84:87]
	s_waitcnt lgkmcnt(2)
	v_mfma_f32_16x16x32_bf16 v[80:83], v[98:101], v[118:121], v[80:83]
	s_waitcnt lgkmcnt(1)
	v_mfma_f32_16x16x32_bf16 v[76:79], v[98:101], v[122:125], v[76:79]
	s_waitcnt lgkmcnt(0)
	v_mfma_f32_16x16x32_bf16 v[72:75], v[98:101], v[126:129], v[72:75]
	v_mfma_f32_16x16x32_bf16 v[68:71], v[102:105], v[114:117], v[68:71]
	v_mfma_f32_16x16x32_bf16 v[64:67], v[102:105], v[118:121], v[64:67]
	v_mfma_f32_16x16x32_bf16 v[60:63], v[102:105], v[122:125], v[60:63]
	v_mfma_f32_16x16x32_bf16 v[56:59], v[102:105], v[126:129], v[56:59]
	v_mfma_f32_16x16x32_bf16 v[52:55], v[106:109], v[114:117], v[52:55]
	v_mfma_f32_16x16x32_bf16 v[48:51], v[106:109], v[118:121], v[48:51]
	v_mfma_f32_16x16x32_bf16 v[44:47], v[106:109], v[122:125], v[44:47]
	v_mfma_f32_16x16x32_bf16 v[40:43], v[106:109], v[126:129], v[40:43]
	v_mfma_f32_16x16x32_bf16 v[36:39], v[110:113], v[114:117], v[36:39]
	v_mfma_f32_16x16x32_bf16 v[28:31], v[110:113], v[118:121], v[28:31]
	v_mfma_f32_16x16x32_bf16 v[20:23], v[110:113], v[122:125], v[20:23]
	v_mfma_f32_16x16x32_bf16 v[8:11], v[110:113], v[126:129], v[8:11]
	s_setprio 0
	s_andn2_b64 vcc, exec, s[18:19]
	s_cbranch_vccnz .LBB0_452
	s_bitcmp1_b32 s3, 0
	s_cselect_b32 s1, 0xf000, 0
	v_add_u32_e32 v97, s1, v94
	s_waitcnt vmcnt(5)
	ds_write_b128 v97, v[0:3]
	s_waitcnt vmcnt(4)
	ds_write_b128 v97, v[4:7] offset:10240
	s_waitcnt vmcnt(3)
	ds_write_b128 v97, v[12:15] offset:20480
	s_waitcnt vmcnt(2)
	ds_write_b128 v97, v[16:19] offset:30720
	s_waitcnt vmcnt(1)
	ds_write_b128 v97, v[24:27] offset:40960
	s_waitcnt vmcnt(0)
	ds_write_b128 v97, v[32:35] offset:51200
	s_branch .LBB0_452

; __device__ __forceinline__ int tidx() { int t = threadIdx.x; asm volatile("" : "+v"(t)); return t; }
; template <int NT, bool LOWREG = false>
; __device__ __forceinline__ void gemm_mainloop(const bh* __restrict__ A, long lda, const bh* __restrict__ B, long ldb, int K,
;                                               char* lds, f32x4 (&acc)[4][NT]) {
;     ...
;   const int tid = tidx(), lane = tid & 63, wid = tid >> 6, wr = wid >> 1, wc = wid & 1, fr = lane & 15, fq = lane >> 4;
;   const int srow = tid >> 3, scol = (tid & 7) * 8;
;   const bh* Ap = A + (long)srow * lda + scol;
;   const bh* Bp = B + (long)srow * ldb + scol;
;   bf16x8 ra[4], rb[NB];
;   const int nk = K >> 6;
; #pragma unroll
;   for (int i = 0; i < 4; ++i) ra[i] = *reinterpret_cast<const bf16x8*>(Ap + (long)(64 * i) * lda);
; #pragma unroll
;   for (int i = 0; i < NB; ++i) rb[i] = *reinterpret_cast<const bf16x8*>(Bp + (long)(64 * i) * ldb);
; #pragma unroll
;   for (int i = 0; i < 4; ++i) *reinterpret_cast<bf16x8*>(lds + (srow + 64 * i) * LROW + scol * 2) = ra[i];
; #pragma unroll
;   for (int i = 0; i < NB; ++i) *reinterpret_cast<bf16x8*>(lds + A_BYTES + (srow + 64 * i) * LROW + scol * 2) = rb[i];
;   __syncthreads();
; __device__ __forceinline__ void merge_phase(const bh* __restrict__ ys, const bh* __restrict__ G, const bh* __restrict__ Wb,
;                             const float* __restrict__ ssp, bh* __restrict__ merged, char* lds) {
;     ...
;     for (int n = 0; n < 4; ++n) {
;       f32x4 accP[4][4];
; #pragma unroll
;       for (int m = 0; m < 4; ++m)
; #pragma unroll
;         for (int q = 0; q < 4; ++q) accP[m][q] = f32x4{0.f, 0.f, 0.f, 0.f};
;       gemm_mainloop<4, true>(ys + (long)tm * 256 * 2048 + n * 512, 2048, Wb + ((long)n * 1024 + tn * 128) * 512, 512, 512, lds, accP);
.LBB0_794:
	v_mov_b32_e32 v32, v188
	s_lshl_b32 s52, s20, 10
	s_add_u32 s8, s17, s52
	v_ashrrev_i32_e32 v22, 3, v32
	v_ashrrev_i32_e32 v23, 31, v22
	s_addc_u32 s9, s18, 0
	v_lshlrev_b64 v[28:29], 12, v[22:23]
	v_lshlrev_b32_e32 v2, 4, v32
	v_lshl_add_u64 v[0:1], s[8:9], 0, v[28:29]
	v_and_b32_e32 v176, 0x70, v2
	v_lshl_add_u64 v[0:1], v[0:1], 0, v[176:177]
	s_mov_b32 s8, 0x40000
	s_add_u32 s10, s52, s6
	v_add_co_u32_e32 v4, vcc, s8, v0
	s_addc_u32 s11, 0, s7
	s_nop 0
	v_addc_co_u32_e32 v5, vcc, 0, v1, vcc
	s_mov_b32 s8, 0x80000
	s_lshl_b64 s[10:11], s[10:11], 10
	global_load_dwordx4 v[64:67], v[0:1], off
	global_load_dwordx4 v[68:71], v[4:5], off
	v_add_co_u32_e32 v4, vcc, s8, v0
	s_add_u32 s10, s12, s10
	s_nop 0
	v_addc_co_u32_e32 v5, vcc, 0, v1, vcc
	s_mov_b32 s8, 0xc0000
	s_addc_u32 s11, s13, s11
	v_lshlrev_b64 v[30:31], 10, v[22:23]
	v_add_co_u32_e32 v0, vcc, s8, v0
	v_lshl_add_u64 v[2:3], s[10:11], 0, v[30:31]
	s_nop 0
	v_addc_co_u32_e32 v1, vcc, 0, v1, vcc
	global_load_dwordx4 v[72:75], v[4:5], off
	global_load_dwordx4 v[76:79], v[0:1], off
	v_lshl_add_u64 v[0:1], v[2:3], 0, v[176:177]
	s_mov_b32 s8, 0x10000
	v_add_co_u32_e32 v2, vcc, s8, v0
	v_and_b32_e32 v23, 15, v32
	s_nop 0
	v_addc_co_u32_e32 v3, vcc, 0, v1, vcc
	global_load_dwordx4 v[80:83], v[0:1], off
	global_load_dwordx4 v[84:87], v[2:3], off
	v_lshrrev_b32_e32 v33, 1, v32
	s_mov_b32 s10, 0x7ffffc0
	s_mov_b32 s53, s49
	v_and_b32_e32 v223, 48, v32
	v_and_b32_e32 v32, 0x4f, v32
	v_mul_lo_u32 v22, v22, s73
	v_and_or_b32 v23, v33, s10, v23
	v_or_b32_e32 v28, v28, v176
	v_or_b32_e32 v30, v30, v176
	s_mov_b64 s[48:49], s[52:53]
	s_mov_b64 s[8:9], 0
	s_mov_b32 s21, 0
	v_mov_b32_e32 v12, 0
	v_mov_b32_e32 v13, v222
	v_mov_b32_e32 v14, v222
	v_mov_b32_e32 v15, v222
	v_mov_b32_e32 v0, 0
	v_mov_b32_e32 v1, v222
	v_mov_b32_e32 v2, v222
	v_mov_b32_e32 v3, v222
	v_mov_b32_e32 v4, 0
	v_mov_b32_e32 v5, v222
	v_mov_b32_e32 v6, v222
	v_mov_b32_e32 v7, v222
	v_mov_b32_e32 v8, 0
	v_mov_b32_e32 v9, v222
	v_mov_b32_e32 v10, v222
	v_mov_b32_e32 v11, v222
	v_mov_b32_e32 v24, 0
	v_mov_b32_e32 v25, v222
	v_mov_b32_e32 v26, v222
	v_mov_b32_e32 v27, v222
	v_mov_b32_e32 v16, 0
	v_mov_b32_e32 v17, v222
	v_mov_b32_e32 v18, v222
	v_mov_b32_e32 v19, v222
	v_mov_b32_e32 v20, 0
	v_mov_b32_e32 v21, v222
	v_mul_u32_u24_e32 v224, 0xa0, v32
	v_add3_u32 v225, 32, v176, v22
	v_mul_lo_u32 v226, v23, s73
	v_lshl_add_u64 v[184:185], s[2:3], 0, v[28:29]
	v_lshl_add_u64 v[186:187], s[4:5], 0, v[30:31]
	v_mov_b32_e32 v22, v222
	v_mov_b32_e32 v23, v222
	v_mov_b32_e32 v28, 0
	v_mov_b32_e32 v29, v222
	v_mov_b32_e32 v30, v222
	v_mov_b32_e32 v31, v222
	v_mov_b32_e32 v44, 0
	v_mov_b32_e32 v45, v222
	v_mov_b32_e32 v46, v222
	v_mov_b32_e32 v47, v222
	v_mov_b32_e32 v32, 0
	v_mov_b32_e32 v33, v222
	v_mov_b32_e32 v34, v222
	v_mov_b32_e32 v35, v222
	v_mov_b32_e32 v36, 0
	v_mov_b32_e32 v37, v222
	v_mov_b32_e32 v38, v222
	v_mov_b32_e32 v39, v222
	v_mov_b32_e32 v40, 0
	v_mov_b32_e32 v41, v222
	v_mov_b32_e32 v42, v222
	v_mov_b32_e32 v43, v222
	v_mov_b32_e32 v56, 0
	v_mov_b32_e32 v57, v222
	v_mov_b32_e32 v58, v222
	v_mov_b32_e32 v59, v222
	v_mov_b32_e32 v48, 0
	v_mov_b32_e32 v49, v222
	v_mov_b32_e32 v50, v222
	v_mov_b32_e32 v51, v222
	v_mov_b32_e32 v52, 0
	v_mov_b32_e32 v53, v222
	v_mov_b32_e32 v54, v222
	v_mov_b32_e32 v55, v222
	v_mov_b32_e32 v60, 0
	v_mov_b32_e32 v61, v222
	v_mov_b32_e32 v62, v222
	v_mov_b32_e32 v63, v222
	s_waitcnt vmcnt(5)
	ds_write_b128 v225, v[64:67]
	s_waitcnt vmcnt(4)
	ds_write_b128 v225, v[68:71] offset:10240
	s_waitcnt vmcnt(3)
	ds_write_b128 v225, v[72:75] offset:20480
	s_waitcnt vmcnt(2)
	ds_write_b128 v225, v[76:79] offset:30720
	s_waitcnt vmcnt(1)
	ds_write_b128 v225, v[80:83] offset:40960
	s_waitcnt vmcnt(0)
	ds_write_b128 v225, v[84:87] offset:51200
	s_waitcnt vmcnt(3)
	v_lshl_add_u64 v[72:73], v[184:185], 0, s[8:9]
	v_add_co_u32_e32 v64, vcc, 0x18f70000, v72
	s_waitcnt vmcnt(1)
	v_lshl_add_u64 v[80:81], v[186:187], 0, s[8:9]
	v_addc_co_u32_e32 v65, vcc, 0, v73, vcc
	v_add_co_u32_e32 v68, vcc, 0x18fb0000, v72
	s_nop 1
	v_addc_co_u32_e32 v69, vcc, 0, v73, vcc
	v_add_co_u32_e32 v74, vcc, 0x18ff0000, v72
	global_load_dwordx4 v[64:67], v[64:65], off offset:128
	s_nop 0
	global_load_dwordx4 v[68:71], v[68:69], off offset:128
	v_addc_co_u32_e32 v75, vcc, 0, v73, vcc
	v_add_co_u32_e32 v76, vcc, 0x19030000, v72
	s_nop 1
	v_addc_co_u32_e32 v77, vcc, 0, v73, vcc
	v_add_co_u32_e32 v82, vcc, 0x1058000, v80
	global_load_dwordx4 v[72:75], v[74:75], off offset:128
	s_nop 0
	global_load_dwordx4 v[76:79], v[76:77], off offset:128
	v_addc_co_u32_e32 v83, vcc, 0, v81, vcc
	s_waitcnt vmcnt(4)
	v_add_co_u32_e32 v84, vcc, 0x1068000, v80
	s_nop 1
	v_addc_co_u32_e32 v85, vcc, 0, v81, vcc
	global_load_dwordx4 v[80:83], v[82:83], off offset:128
	s_nop 0
	global_load_dwordx4 v[84:87], v[84:85], off offset:128
	s_waitcnt lgkmcnt(0)
	s_barrier
	s_branch .LBB0_796
; template <int NT, bool LOWREG = false>
; __device__ __forceinline__ void gemm_mainloop(const bh* __restrict__ A, long lda, const bh* __restrict__ B, long ldb, int K,
;                                               char* lds, f32x4 (&acc)[4][NT]) {
;     ...
;   for (int kt = 0; kt < nk; ++kt) {
;     const bool more = kt + 1 < nk;
;     if (more) {
; #pragma unroll
;       for (int i = 0; i < 4; ++i) ra[i] = *reinterpret_cast<const bf16x8*>(Ap + (long)(64 * i) * lda + (kt + 1) * 64);
; #pragma unroll
;       for (int i = 0; i < NB; ++i) rb[i] = *reinterpret_cast<const bf16x8*>(Bp + (long)(64 * i) * ldb + (kt + 1) * 64);
;     }
;     const char* sb = lds + (kt & 1) * STAGE;
;     const char* a_base = sb + (wr * 64 + fr) * LROW + fq * 16;
;     const char* b_base = sb + A_BYTES + (wc * (16 * NT) + fr) * LROW + fq * 16;
; #pragma unroll
;     for (int ks = 0; ks < 2; ++ks) {
;       if constexpr (LOWREG) {
;         bf16x8 bfr[NT];
; #pragma unroll
;         for (int n = 0; n < NT; ++n) bfr[n] = *reinterpret_cast<const bf16x8*>(b_base + n * 16 * LROW + ks * 64);
; #pragma unroll
;         for (int mp = 0; mp < 2; ++mp) {
;           bf16x8 af[2];
; #pragma unroll
;           for (int m = 0; m < 2; ++m) af[m] = *reinterpret_cast<const bf16x8*>(a_base + (mp * 2 + m) * 16 * LROW + ks * 64);
;           __builtin_amdgcn_s_setprio(1);
; #pragma unroll
;           for (int m = 0; m < 2; ++m)
; #pragma unroll
;             for (int n = 0; n < NT; ++n) acc[mp * 2 + m][n] = mfma16(af[m], bfr[n], acc[mp * 2 + m][n]);
;           __builtin_amdgcn_s_setprio(0);
;         }
;       } else {
;       bf16x8 af[4], bfr[NT];
; #pragma unroll
;       for (int m = 0; m < 4; ++m) af[m] = *reinterpret_cast<const bf16x8*>(a_base + m * 16 * LROW + ks * 64);
; #pragma unroll
;       for (int n = 0; n < NT; ++n) bfr[n] = *reinterpret_cast<const bf16x8*>(b_base + n * 16 * LROW + ks * 64);
;       __builtin_amdgcn_s_setprio(1);
; #pragma unroll
;       for (int m = 0; m < 4; ++m)
; #pragma unroll
;         for (int n = 0; n < NT; ++n) acc[m][n] = mfma16(af[m], bfr[n], acc[m][n]);
;       __builtin_amdgcn_s_setprio(0);
;       }
;     }
;     if (more) {
;       char* wb = lds + ((kt + 1) & 1) * STAGE;
; #pragma unroll
;       for (int i = 0; i < 4; ++i) *reinterpret_cast<bf16x8*>(wb + (srow + 64 * i) * LROW + scol * 2) = ra[i];
; #pragma unroll
.LBB0_795:
	s_add_u32 s8, s8, 0x80
	s_addc_u32 s9, s9, 0
	s_cmpk_ge_i32 s8, 0x380
	s_cbranch_scc1 .Lmy_t14g_skip_795
	s_waitcnt vmcnt(3)
	v_lshl_add_u64 v[72:73], v[184:185], 0, s[8:9]
	v_add_co_u32_e32 v64, vcc, 0x18f70000, v72
	s_waitcnt vmcnt(1)
	v_lshl_add_u64 v[80:81], v[186:187], 0, s[8:9]
	v_addc_co_u32_e32 v65, vcc, 0, v73, vcc
	v_add_co_u32_e32 v68, vcc, 0x18fb0000, v72
	s_nop 1
	v_addc_co_u32_e32 v69, vcc, 0, v73, vcc
	v_add_co_u32_e32 v74, vcc, 0x18ff0000, v72
	global_load_dwordx4 v[64:67], v[64:65], off offset:128
	s_nop 0
	global_load_dwordx4 v[68:71], v[68:69], off offset:128
	v_addc_co_u32_e32 v75, vcc, 0, v73, vcc
	v_add_co_u32_e32 v76, vcc, 0x19030000, v72
	s_nop 1
	v_addc_co_u32_e32 v77, vcc, 0, v73, vcc
	v_add_co_u32_e32 v82, vcc, 0x1058000, v80
	global_load_dwordx4 v[72:75], v[74:75], off offset:128
	s_nop 0
	global_load_dwordx4 v[76:79], v[76:77], off offset:128
	v_addc_co_u32_e32 v83, vcc, 0, v81, vcc
	s_waitcnt vmcnt(4)
	v_add_co_u32_e32 v84, vcc, 0x1068000, v80
	s_nop 1
	v_addc_co_u32_e32 v85, vcc, 0, v81, vcc
	global_load_dwordx4 v[80:83], v[82:83], off offset:128
	s_nop 0
	global_load_dwordx4 v[84:87], v[84:85], off offset:128
.Lmy_t14g_skip_795:
	s_cmpk_lg_i32 s8, 0x400
	s_mov_b32 s21, s22
	s_waitcnt lgkmcnt(0)
	s_barrier
	s_cbranch_scc0 .LBB0_800
.LBB0_796:
	s_cmpk_lg_i32 s8, 0x380
	s_cselect_b64 s[10:11], -1, 0
	s_cmpk_eq_i32 s8, 0x380
	s_cbranch_scc1 .Lmy_merge_pref
.LBB0_798:
	s_add_i32 s22, s21, 1
	s_bitcmp1_b32 s21, 0
	s_cselect_b32 s21, 0xf000, 0
	s_add_i32 s21, s21, 32
	v_add3_u32 v227, s21, v224, v223
	v_add3_u32 v176, s21, v226, v223
	ds_read_b128 v[198:201], v227 offset:40960
	ds_read_b128 v[228:231], v227 offset:43520
	ds_read_b128 v[232:235], v227 offset:46080
	ds_read_b128 v[236:239], v227 offset:48640
	ds_read_b128 v[240:243], v176
	ds_read_b128 v[244:247], v176 offset:2560
	s_setprio 1
	s_waitcnt lgkmcnt(1)
	v_mfma_f32_16x16x32_bf16 v[60:63], v[240:243], v[198:201], v[60:63]
	v_mfma_f32_16x16x32_bf16 v[52:55], v[240:243], v[228:231], v[52:55]
	v_mfma_f32_16x16x32_bf16 v[48:51], v[240:243], v[232:235], v[48:51]
	v_mfma_f32_16x16x32_bf16 v[56:59], v[240:243], v[236:239], v[56:59]
	s_waitcnt lgkmcnt(0)
	v_mfma_f32_16x16x32_bf16 v[40:43], v[244:247], v[198:201], v[40:43]
	v_mfma_f32_16x16x32_bf16 v[36:39], v[244:247], v[228:231], v[36:39]
	v_mfma_f32_16x16x32_bf16 v[32:35], v[244:247], v[232:235], v[32:35]
	v_mfma_f32_16x16x32_bf16 v[44:47], v[244:247], v[236:239], v[44:47]
	s_setprio 0
	ds_read_b128 v[240:243], v176 offset:5120
	ds_read_b128 v[244:247], v176 offset:7680
	s_setprio 1
	s_waitcnt lgkmcnt(1)
	v_mfma_f32_16x16x32_bf16 v[28:31], v[240:243], v[198:201], v[28:31]
	v_mfma_f32_16x16x32_bf16 v[20:23], v[240:243], v[228:231], v[20:23]
	v_mfma_f32_16x16x32_bf16 v[16:19], v[240:243], v[232:235], v[16:19]
	v_mfma_f32_16x16x32_bf16 v[24:27], v[240:243], v[236:239], v[24:27]
	s_waitcnt lgkmcnt(0)
	v_mfma_f32_16x16x32_bf16 v[8:11], v[244:247], v[198:201], v[8:11]
	v_mfma_f32_16x16x32_bf16 v[4:7], v[244:247], v[228:231], v[4:7]
	v_mfma_f32_16x16x32_bf16 v[0:3], v[244:247], v[232:235], v[0:3]
	v_mfma_f32_16x16x32_bf16 v[12:15], v[244:247], v[236:239], v[12:15]
	s_setprio 0
	ds_read_b128 v[198:201], v227 offset:41024
	ds_read_b128 v[228:231], v227 offset:43584
	ds_read_b128 v[232:235], v227 offset:46144
	ds_read_b128 v[236:239], v227 offset:48704
	ds_read_b128 v[240:243], v176 offset:64
	ds_read_b128 v[244:247], v176 offset:2624
	s_setprio 1
	s_waitcnt lgkmcnt(1)
	v_mfma_f32_16x16x32_bf16 v[60:63], v[240:243], v[198:201], v[60:63]
	v_mfma_f32_16x16x32_bf16 v[52:55], v[240:243], v[228:231], v[52:55]
	v_mfma_f32_16x16x32_bf16 v[48:51], v[240:243], v[232:235], v[48:51]
	v_mfma_f32_16x16x32_bf16 v[56:59], v[240:243], v[236:239], v[56:59]
	s_waitcnt lgkmcnt(0)
	v_mfma_f32_16x16x32_bf16 v[40:43], v[244:247], v[198:201], v[40:43]
	v_mfma_f32_16x16x32_bf16 v[36:39], v[244:247], v[228:231], v[36:39]
	v_mfma_f32_16x16x32_bf16 v[32:35], v[244:247], v[232:235], v[32:35]
	v_mfma_f32_16x16x32_bf16 v[44:47], v[244:247], v[236:239], v[44:47]
	s_setprio 0
	ds_read_b128 v[240:243], v176 offset:5184
	ds_read_b128 v[244:247], v176 offset:7744
	s_setprio 1
	s_waitcnt lgkmcnt(1)
	v_mfma_f32_16x16x32_bf16 v[28:31], v[240:243], v[198:201], v[28:31]
	v_mfma_f32_16x16x32_bf16 v[20:23], v[240:243], v[228:231], v[20:23]
	v_mfma_f32_16x16x32_bf16 v[16:19], v[240:243], v[232:235], v[16:19]
	v_mfma_f32_16x16x32_bf16 v[24:27], v[240:243], v[236:239], v[24:27]
	s_waitcnt lgkmcnt(0)
	v_mfma_f32_16x16x32_bf16 v[8:11], v[244:247], v[198:201], v[8:11]
	v_mfma_f32_16x16x32_bf16 v[4:7], v[244:247], v[228:231], v[4:7]
	v_mfma_f32_16x16x32_bf16 v[0:3], v[244:247], v[232:235], v[0:3]
	v_mfma_f32_16x16x32_bf16 v[12:15], v[244:247], v[236:239], v[12:15]
	s_setprio 0
	s_andn2_b64 vcc, exec, s[10:11]
	s_cbranch_vccnz .LBB0_795
	s_bitcmp1_b32 s22, 0
	s_cselect_b32 s10, 0xf000, 0
	v_add_u32_e32 v176, s10, v225
	s_waitcnt vmcnt(5)
	ds_write_b128 v176, v[64:67]
	s_waitcnt vmcnt(4)
	ds_write_b128 v176, v[68:71] offset:10240
	s_waitcnt vmcnt(3)
	ds_write_b128 v176, v[72:75] offset:20480
	s_waitcnt vmcnt(2)
	ds_write_b128 v176, v[76:79] offset:30720
	s_waitcnt vmcnt(1)
	ds_write_b128 v176, v[80:83] offset:40960
	s_waitcnt vmcnt(0)
	ds_write_b128 v176, v[84:87] offset:51200
	s_branch .LBB0_795

; __device__ __forceinline__ int tidx() { int t = threadIdx.x; asm volatile("" : "+v"(t)); return t; }
; template <int NT, bool LOWREG = false>
; __device__ __forceinline__ void gemm_mainloop(const bh* __restrict__ A, long lda, const bh* __restrict__ B, long ldb, int K,
;                                               char* lds, f32x4 (&acc)[4][NT]) {
;     ...
;   const int tid = tidx(), lane = tid & 63, wid = tid >> 6, wr = wid >> 1, wc = wid & 1, fr = lane & 15, fq = lane >> 4;
;   const int srow = tid >> 3, scol = (tid & 7) * 8;
;   const bh* Ap = A + (long)srow * lda + scol;
;   const bh* Bp = B + (long)srow * ldb + scol;
;   bf16x8 ra[4], rb[NB];
;   const int nk = K >> 6;
; #pragma unroll
;   for (int i = 0; i < 4; ++i) ra[i] = *reinterpret_cast<const bf16x8*>(Ap + (long)(64 * i) * lda);
; #pragma unroll
;   for (int i = 0; i < NB; ++i) rb[i] = *reinterpret_cast<const bf16x8*>(Bp + (long)(64 * i) * ldb);
; #pragma unroll
;   for (int i = 0; i < 4; ++i) *reinterpret_cast<bf16x8*>(lds + (srow + 64 * i) * LROW + scol * 2) = ra[i];
; #pragma unroll
;   for (int i = 0; i < NB; ++i) *reinterpret_cast<bf16x8*>(lds + A_BYTES + (srow + 64 * i) * LROW + scol * 2) = rb[i];
;   __syncthreads();
;     ...
;   for (int tile = (t_first >= 0 ? t_first : (int)blockIdx.x); tile < tm_n * tn_n; tile += (t_first >= 0 ? t_stride : (int)gridDim.x)) {
;     const int tn = tile / tm_n, tm = tile - tn * tm_n;
;     f32x4 acc[4][NT];
; #pragma unroll
;     for (int m = 0; m < 4; ++m)
; #pragma unroll
;       for (int n = 0; n < NT; ++n) acc[m][n] = f32x4{0.f, 0.f, 0.f, 0.f};
;     gemm_mainloop<NT>(A + (long)tm * 256 * lda, lda, Bt + (long)tn * BN * ldb, ldb, K, lds, acc);
.LBB0_931:
	s_ashr_i32 s3, s2, 31
	s_lshl_b64 s[14:15], s[2:3], 19
	s_lshr_b32 s3, s3, 26
	s_add_i32 s3, s2, s3
	s_and_b32 s4, s3, 0xffffffc0
	s_sub_i32 s10, s2, s4
	s_ashr_i32 s11, s10, 31
	v_mov_b32_e32 v19, v188
	s_ashr_i32 s12, s3, 6
	s_lshl_b64 s[16:17], s[10:11], 19
	s_add_u32 s20, s38, s16
	v_ashrrev_i32_e32 v32, 3, v19
	v_ashrrev_i32_e32 v33, 31, v32
	s_addc_u32 s21, s39, s17
	v_lshlrev_b64 v[34:35], 11, v[32:33]
	v_lshlrev_b32_e32 v2, 4, v19
	v_lshl_add_u64 v[0:1], s[20:21], 0, v[34:35]
	v_and_b32_e32 v176, 0x70, v2
	v_lshl_add_u64 v[0:1], v[0:1], 0, v[176:177]
	s_mov_b32 s3, 0x20000
	v_add_co_u32_e32 v4, vcc, s3, v0
	s_ashr_i32 s13, s12, 31
	s_nop 0
	v_addc_co_u32_e32 v5, vcc, 0, v1, vcc
	s_mov_b32 s3, 0x40000
	s_lshl_b64 s[16:17], s[12:13], 17
	global_load_dwordx4 v[20:23], v[0:1], off
	global_load_dwordx4 v[24:27], v[4:5], off
	v_add_co_u32_e32 v4, vcc, s3, v0
	s_add_u32 s12, s18, s16
	s_nop 0
	v_addc_co_u32_e32 v5, vcc, 0, v1, vcc
	s_mov_b32 s3, 0x60000
	s_addc_u32 s13, s19, s17
	v_add_co_u32_e32 v0, vcc, s3, v0
	v_lshl_add_u64 v[2:3], s[12:13], 0, v[34:35]
	s_nop 0
	v_addc_co_u32_e32 v1, vcc, 0, v1, vcc
	global_load_dwordx4 v[28:31], v[4:5], off
	global_load_dwordx4 v[36:39], v[0:1], off
	v_lshl_add_u64 v[0:1], v[2:3], 0, v[176:177]
	global_load_dwordx4 v[40:43], v[0:1], off
	v_and_b32_e32 v33, 15, v19
	v_and_b32_e32 v58, 48, v19
	v_lshrrev_b32_e32 v19, 1, v19
	s_mov_b32 s5, 0x7ffffc0
	v_mul_lo_u32 v59, v32, s73
	v_and_or_b32 v32, v19, s5, v33
	v_and_or_b32 v19, v19, 32, v33
	v_mul_lo_u32 v60, v32, s73
	v_lshl_add_u64 v[32:33], s[14:15], 0, v[34:35]
	v_lshl_add_u64 v[34:35], s[16:17], 0, v[34:35]
	s_ashr_i32 s5, s4, 31
	v_mul_u32_u24_e32 v61, 0xa0, v19
	v_or_b32_e32 v19, v32, v176
	v_or_b32_e32 v34, v34, v176
	s_lshl_b64 s[14:15], s[4:5], 19
	v_lshl_add_u64 v[52:53], s[0:1], 0, v[34:35]
	v_mov_b32_e32 v34, s15
	v_subrev_co_u32_e32 v32, vcc, s14, v19
	v_mov_b32_e32 v0, 0
	v_add3_u32 v44, 32, v176, v59
	v_add3_u32 v45, 32, v59, v176
	v_subb_co_u32_e32 v33, vcc, v33, v34, vcc
	s_mov_b32 s3, 0
	s_mov_b64 s[12:13], 0
	v_mov_b32_e32 v1, v0
	v_mov_b32_e32 v2, v0
	v_mov_b32_e32 v3, v0
	v_mov_b32_e32 v4, v0
	v_mov_b32_e32 v5, v0
	v_mov_b32_e32 v6, v0
	v_mov_b32_e32 v7, v0
	v_mov_b32_e32 v8, v0
	v_mov_b32_e32 v9, v0
	v_mov_b32_e32 v10, v0
	v_mov_b32_e32 v11, v0
	v_mov_b32_e32 v12, v0
	v_mov_b32_e32 v13, v0
	v_mov_b32_e32 v14, v0
	v_mov_b32_e32 v15, v0
	v_mov_b32_e32 v16, v0
	v_mov_b32_e32 v17, v0
	v_mov_b32_e32 v18, v0
	v_lshl_add_u64 v[54:55], s[28:29], 0, v[32:33]
	v_mov_b32_e32 v19, v0
	v_mov_b32_e32 v32, v0
	v_mov_b32_e32 v33, v0
	v_mov_b32_e32 v34, v0
	v_mov_b32_e32 v35, v0
	v_mov_b32_e32 v46, v0
	v_mov_b32_e32 v47, v0
	s_waitcnt vmcnt(4)
	ds_write_b128 v44, v[20:23]
	s_waitcnt vmcnt(3)
	ds_write_b128 v44, v[24:27] offset:10240
	s_waitcnt vmcnt(2)
	ds_write_b128 v44, v[28:31] offset:20480
	s_waitcnt vmcnt(1)
	ds_write_b128 v44, v[36:39] offset:30720
	s_waitcnt vmcnt(0)
	ds_write_b128 v45, v[40:43] offset:40960
	v_mov_b32_e32 v44, v0
	v_mov_b32_e32 v45, v0
	v_mov_b32_e32 v48, v0
	v_mov_b32_e32 v49, v0
	v_mov_b32_e32 v50, v0
	v_mov_b32_e32 v51, v0
	s_waitcnt vmcnt(2)
	v_lshl_add_u64 v[28:29], v[54:55], 0, s[12:13]
	v_add_co_u32_e32 v20, vcc, 0x5770000, v28
	s_waitcnt vmcnt(0)
	v_lshl_add_u64 v[40:41], v[52:53], 0, s[12:13]
	v_addc_co_u32_e32 v21, vcc, 0, v29, vcc
	v_add_co_u32_e32 v24, vcc, 0x5790000, v28
	s_nop 1
	v_addc_co_u32_e32 v25, vcc, 0, v29, vcc
	v_add_co_u32_e32 v30, vcc, 0x57b0000, v28
	global_load_dwordx4 v[20:23], v[20:21], off offset:128
	s_nop 0
	global_load_dwordx4 v[24:27], v[24:25], off offset:128
	v_addc_co_u32_e32 v31, vcc, 0, v29, vcc
	v_add_co_u32_e32 v36, vcc, 0x57d0000, v28
	s_nop 1
	v_addc_co_u32_e32 v37, vcc, 0, v29, vcc
	global_load_dwordx4 v[28:31], v[30:31], off offset:128
	s_nop 0
	global_load_dwordx4 v[36:39], v[36:37], off offset:128
	s_nop 0
	global_load_dwordx4 v[40:43], v[40:41], off
	s_waitcnt lgkmcnt(0)
	s_barrier
	s_branch .LBB0_933
; template <int NT, bool LOWREG = false>
; __device__ __forceinline__ void gemm_mainloop(const bh* __restrict__ A, long lda, const bh* __restrict__ B, long ldb, int K,
;                                               char* lds, f32x4 (&acc)[4][NT]) {
;     ...
; #pragma unroll 1
;   for (int kt = 0; kt < nk; ++kt) {
;     const bool more = kt + 1 < nk;
;     if (more) {
; #pragma unroll
;       for (int i = 0; i < 4; ++i) ra[i] = *reinterpret_cast<const bf16x8*>(Ap + (long)(64 * i) * lda + (kt + 1) * 64);
; #pragma unroll
;       for (int i = 0; i < NB; ++i) rb[i] = *reinterpret_cast<const bf16x8*>(Bp + (long)(64 * i) * ldb + (kt + 1) * 64);
;     }
;     const char* sb = lds + (kt & 1) * STAGE;
;     const char* a_base = sb + (wr * 64 + fr) * LROW + fq * 16;
;     const char* b_base = sb + A_BYTES + (wc * (16 * NT) + fr) * LROW + fq * 16;
; #pragma unroll
;     for (int ks = 0; ks < 2; ++ks) {
;       if constexpr (LOWREG) {
;         bf16x8 bfr[NT];
; #pragma unroll
;         for (int n = 0; n < NT; ++n) bfr[n] = *reinterpret_cast<const bf16x8*>(b_base + n * 16 * LROW + ks * 64);
; #pragma unroll
;         for (int mp = 0; mp < 2; ++mp) {
;           bf16x8 af[2];
; #pragma unroll
;           for (int m = 0; m < 2; ++m) af[m] = *reinterpret_cast<const bf16x8*>(a_base + (mp * 2 + m) * 16 * LROW + ks * 64);
;           __builtin_amdgcn_s_setprio(1);
; #pragma unroll
;           for (int m = 0; m < 2; ++m)
; #pragma unroll
;             for (int n = 0; n < NT; ++n) acc[mp * 2 + m][n] = mfma16(af[m], bfr[n], acc[mp * 2 + m][n]);
;           __builtin_amdgcn_s_setprio(0);
;         }
;       } else {
;       bf16x8 af[4], bfr[NT];
; #pragma unroll
;       for (int m = 0; m < 4; ++m) af[m] = *reinterpret_cast<const bf16x8*>(a_base + m * 16 * LROW + ks * 64);
; #pragma unroll
;       for (int n = 0; n < NT; ++n) bfr[n] = *reinterpret_cast<const bf16x8*>(b_base + n * 16 * LROW + ks * 64);
;       __builtin_amdgcn_s_setprio(1);
; #pragma unroll
;       for (int m = 0; m < 4; ++m)
; #pragma unroll
;         for (int n = 0; n < NT; ++n) acc[m][n] = mfma16(af[m], bfr[n], acc[m][n]);
;       __builtin_amdgcn_s_setprio(0);
;       }
;     }
;     if (more) {
;       char* wb = lds + ((kt + 1) & 1) * STAGE;
; #pragma unroll
;       for (int i = 0; i < 4; ++i) *reinterpret_cast<bf16x8*>(wb + (srow + 64 * i) * LROW + scol * 2) = ra[i];
; #pragma unroll
.LBB0_932:
	s_add_u32 s12, s12, 0x80
	s_addc_u32 s13, s13, 0
	s_cmpk_ge_i32 s12, 0x780
	s_cbranch_scc1 .Lmy_t14g_skip_932
	s_waitcnt vmcnt(2)
	v_lshl_add_u64 v[28:29], v[54:55], 0, s[12:13]
	v_add_co_u32_e32 v20, vcc, 0x5770000, v28
	s_waitcnt vmcnt(0)
	v_lshl_add_u64 v[40:41], v[52:53], 0, s[12:13]
	v_addc_co_u32_e32 v21, vcc, 0, v29, vcc
	v_add_co_u32_e32 v24, vcc, 0x5790000, v28
	s_nop 1
	v_addc_co_u32_e32 v25, vcc, 0, v29, vcc
	v_add_co_u32_e32 v30, vcc, 0x57b0000, v28
	global_load_dwordx4 v[20:23], v[20:21], off offset:128
	s_nop 0
	global_load_dwordx4 v[24:27], v[24:25], off offset:128
	v_addc_co_u32_e32 v31, vcc, 0, v29, vcc
	v_add_co_u32_e32 v36, vcc, 0x57d0000, v28
	s_nop 1
	v_addc_co_u32_e32 v37, vcc, 0, v29, vcc
	global_load_dwordx4 v[28:31], v[30:31], off offset:128
	s_nop 0
	global_load_dwordx4 v[36:39], v[36:37], off offset:128
	s_nop 0
	global_load_dwordx4 v[40:43], v[40:41], off
.Lmy_t14g_skip_932:
	s_cmpk_lg_i32 s12, 0x800
	s_mov_b32 s3, s5
	s_waitcnt lgkmcnt(0)
	s_barrier
	s_cbranch_scc0 .LBB0_930
.LBB0_933:
	s_cmpk_lg_i32 s12, 0x780
	s_cselect_b64 s[14:15], -1, 0
	s_cmpk_eq_i32 s12, 0x780
	s_cbranch_scc1 .LBB0_935
.LBB0_935:
	s_add_i32 s5, s3, 1
	s_bitcmp1_b32 s3, 0
	s_cselect_b32 s3, 0xc800, 0
	s_add_i32 s3, s3, 32
	v_add3_u32 v86, s3, v60, v58
	v_add3_u32 v87, s3, v61, v58
	ds_read_b128 v[62:65], v86
	ds_read_b128 v[66:69], v86 offset:2560
	ds_read_b128 v[70:73], v86 offset:5120
	ds_read_b128 v[74:77], v86 offset:7680
	ds_read_b128 v[78:81], v87 offset:40960
	ds_read_b128 v[82:85], v87 offset:43520
	s_setprio 1
	s_waitcnt lgkmcnt(1)
	v_mfma_f32_16x16x32_bf16 v[48:51], v[62:65], v[78:81], v[48:51]
	s_waitcnt lgkmcnt(0)
	v_mfma_f32_16x16x32_bf16 v[44:47], v[62:65], v[82:85], v[44:47]
	v_mfma_f32_16x16x32_bf16 v[32:35], v[66:69], v[78:81], v[32:35]
	v_mfma_f32_16x16x32_bf16 v[16:19], v[66:69], v[82:85], v[16:19]
	v_mfma_f32_16x16x32_bf16 v[12:15], v[70:73], v[78:81], v[12:15]
	v_mfma_f32_16x16x32_bf16 v[8:11], v[70:73], v[82:85], v[8:11]
	v_mfma_f32_16x16x32_bf16 v[4:7], v[74:77], v[78:81], v[4:7]
	v_mfma_f32_16x16x32_bf16 v[0:3], v[74:77], v[82:85], v[0:3]
	s_setprio 0
	ds_read_b128 v[62:65], v86 offset:64
	ds_read_b128 v[66:69], v86 offset:2624
	ds_read_b128 v[70:73], v86 offset:5184
	ds_read_b128 v[74:77], v86 offset:7744
	ds_read_b128 v[78:81], v87 offset:41024
	ds_read_b128 v[82:85], v87 offset:43584
	s_setprio 1
	s_waitcnt lgkmcnt(1)
	v_mfma_f32_16x16x32_bf16 v[48:51], v[62:65], v[78:81], v[48:51]
	s_waitcnt lgkmcnt(0)
	v_mfma_f32_16x16x32_bf16 v[44:47], v[62:65], v[82:85], v[44:47]
	v_mfma_f32_16x16x32_bf16 v[32:35], v[66:69], v[78:81], v[32:35]
	v_mfma_f32_16x16x32_bf16 v[16:19], v[66:69], v[82:85], v[16:19]
	v_mfma_f32_16x16x32_bf16 v[12:15], v[70:73], v[78:81], v[12:15]
	v_mfma_f32_16x16x32_bf16 v[8:11], v[70:73], v[82:85], v[8:11]
	v_mfma_f32_16x16x32_bf16 v[4:7], v[74:77], v[78:81], v[4:7]
	v_mfma_f32_16x16x32_bf16 v[0:3], v[74:77], v[82:85], v[0:3]
	s_setprio 0
	s_andn2_b64 vcc, exec, s[14:15]
	s_cbranch_vccnz .LBB0_932
	s_bitcmp1_b32 s5, 0
	s_cselect_b32 s3, 0xc800, 0
	s_add_i32 s3, s3, 32
	v_add3_u32 v62, s3, v176, v59
	s_waitcnt vmcnt(4)
	ds_write_b128 v62, v[20:23]
	s_waitcnt vmcnt(3)
	ds_write_b128 v62, v[24:27] offset:10240
	s_waitcnt vmcnt(2)
	ds_write_b128 v62, v[28:31] offset:20480
	s_waitcnt vmcnt(1)
	ds_write_b128 v62, v[36:39] offset:30720
	v_add3_u32 v62, s3, v59, v176
	s_waitcnt vmcnt(0)
	ds_write_b128 v62, v[40:43] offset:40960
	s_branch .LBB0_932

; __device__ __forceinline__ int tidx() { int t = threadIdx.x; asm volatile("" : "+v"(t)); return t; }
; template <int NT, bool LOWREG = false>
; __device__ __forceinline__ void gemm_mainloop(const bh* __restrict__ A, long lda, const bh* __restrict__ B, long ldb, int K,
;                                               char* lds, f32x4 (&acc)[4][NT]) {
;     ...
;   const int tid = tidx(), lane = tid & 63, wid = tid >> 6, wr = wid >> 1, wc = wid & 1, fr = lane & 15, fq = lane >> 4;
;   const int srow = tid >> 3, scol = (tid & 7) * 8;
;   const bh* Ap = A + (long)srow * lda + scol;
;   const bh* Bp = B + (long)srow * ldb + scol;
;   bf16x8 ra[4], rb[NB];
;   const int nk = K >> 6;
; #pragma unroll
;   for (int i = 0; i < 4; ++i) ra[i] = *reinterpret_cast<const bf16x8*>(Ap + (long)(64 * i) * lda);
; #pragma unroll
;   for (int i = 0; i < NB; ++i) rb[i] = *reinterpret_cast<const bf16x8*>(Bp + (long)(64 * i) * ldb);
; #pragma unroll
;   for (int i = 0; i < 4; ++i) *reinterpret_cast<bf16x8*>(lds + (srow + 64 * i) * LROW + scol * 2) = ra[i];
; #pragma unroll
;   for (int i = 0; i < NB; ++i) *reinterpret_cast<bf16x8*>(lds + A_BYTES + (srow + 64 * i) * LROW + scol * 2) = rb[i];
;   __syncthreads();
; #pragma unroll 1
;   for (int kt = 0; kt < nk; ++kt) {
;     const bool more = kt + 1 < nk;
;     if (more) {
; #pragma unroll
;       for (int i = 0; i < 4; ++i) ra[i] = *reinterpret_cast<const bf16x8*>(Ap + (long)(64 * i) * lda + (kt + 1) * 64);
; #pragma unroll
;       for (int i = 0; i < NB; ++i) rb[i] = *reinterpret_cast<const bf16x8*>(Bp + (long)(64 * i) * ldb + (kt + 1) * 64);
;     }
;     ...
;   for (int tile = (t_first >= 0 ? t_first : (int)blockIdx.x); tile < tm_n * tn_n; tile += (t_first >= 0 ? t_stride : (int)gridDim.x)) {
;     const int tn = tile / tm_n, tm = tile - tn * tm_n;
;     f32x4 acc[4][NT];
; #pragma unroll
;     for (int m = 0; m < 4; ++m)
; #pragma unroll
;       for (int n = 0; n < NT; ++n) acc[m][n] = f32x4{0.f, 0.f, 0.f, 0.f};
;     gemm_mainloop<NT>(A + (long)tm * 256 * lda, lda, Bt + (long)tn * BN * ldb, ldb, K, lds, acc);
.LBB0_1130:
	s_ashr_i32 s2, s14, 31
	s_lshr_b32 s2, s2, 26
	s_add_i32 s3, s14, s2
	s_and_b32 s8, s3, 0xffffffc0
	s_sub_i32 s4, s14, s8
	s_ashr_i32 s5, s4, 31
	v_mov_b32_e32 v22, v188
	s_ashr_i32 s2, s3, 6
	s_lshl_b64 s[10:11], s[4:5], 19
	s_add_u32 s10, s38, s10
	v_ashrrev_i32_e32 v8, 3, v22
	v_ashrrev_i32_e32 v9, 31, v8
	s_addc_u32 s11, s39, s11
	v_lshlrev_b64 v[10:11], 11, v[8:9]
	v_lshlrev_b32_e32 v2, 4, v22
	s_ashr_i32 s3, s2, 31
	v_lshl_add_u64 v[0:1], s[10:11], 0, v[10:11]
	v_and_b32_e32 v176, 0x70, v2
	s_lshl_b64 s[16:17], s[2:3], 18
	s_waitcnt vmcnt(10)
	v_lshl_add_u64 v[16:17], v[0:1], 0, v[176:177]
	s_mov_b32 s5, 0x20000
	s_add_u32 s18, s12, s16
	v_add_co_u32_e32 v4, vcc, s5, v16
	s_addc_u32 s19, s13, s17
	s_nop 0
	v_addc_co_u32_e32 v5, vcc, 0, v17, vcc
	s_mov_b32 s9, 0x40000
	v_lshl_add_u64 v[20:21], s[18:19], 0, v[10:11]
	v_add_co_u32_e32 v12, vcc, s9, v16
	s_mov_b32 s9, 0x60000
	s_nop 0
	v_addc_co_u32_e32 v13, vcc, 0, v17, vcc
	v_lshl_add_u64 v[20:21], v[20:21], 0, v[176:177]
	global_load_dwordx4 v[0:3], v[16:17], off
	global_load_dwordx4 v[24:27], v[20:21], off
	v_add_co_u32_e32 v16, vcc, s9, v16
	global_load_dwordx4 v[4:7], v[4:5], off
	s_nop 0
	v_addc_co_u32_e32 v17, vcc, 0, v17, vcc
	v_add_co_u32_e32 v20, vcc, s5, v20
	global_load_dwordx4 v[12:15], v[12:13], off
	s_nop 0
	v_addc_co_u32_e32 v21, vcc, 0, v21, vcc
	global_load_dwordx4 v[16:19], v[16:17], off
	v_mul_lo_u32 v8, v8, s73
	global_load_dwordx4 v[32:35], v[20:21], off
	v_add3_u32 v94, 32, v176, v8
	v_and_b32_e32 v8, 15, v22
	v_lshrrev_b32_e32 v9, 1, v22
	s_mov_b32 s5, 0x7ffffc0
	v_and_or_b32 v8, v9, s5, v8
	v_mul_lo_u32 v95, v8, s73
	v_and_b32_e32 v8, 0x4f, v22
	v_mul_u32_u24_e32 v96, 0xa0, v8
	v_and_b32_e32 v8, 7, v22
	s_ashr_i32 s9, s8, 31
	v_lshl_or_b32 v10, v8, 4, v10
	s_lshl_b64 s[8:9], s[8:9], 19
	v_subrev_co_u32_e32 v8, vcc, s8, v10
	v_mov_b32_e32 v9, s9
	v_readlane_b32 s8, v253, 55
	v_subb_co_u32_e32 v9, vcc, v11, v9, vcc
	v_readlane_b32 s9, v253, 56
	s_add_u32 s8, s8, s16
	v_lshl_add_u64 v[88:89], s[0:1], 0, v[8:9]
	s_addc_u32 s9, s9, s17
	v_mov_b32_e32 v8, 0
	s_mov_b32 s3, 0
	v_and_b32_e32 v93, 48, v22
	v_lshl_add_u64 v[90:91], s[8:9], 0, v[10:11]
	s_mov_b64 s[8:9], 0
	v_mov_b32_e32 v9, v8
	v_mov_b32_e32 v10, v8
	v_mov_b32_e32 v11, v8
	v_mov_b32_e32 v20, v8
	v_mov_b32_e32 v21, v8
	v_mov_b32_e32 v22, v8
	v_mov_b32_e32 v23, v8
	v_mov_b32_e32 v28, v8
	v_mov_b32_e32 v29, v8
	v_mov_b32_e32 v30, v8
	v_mov_b32_e32 v31, v8
	v_mov_b32_e32 v36, v8
	v_mov_b32_e32 v37, v8
	v_mov_b32_e32 v38, v8
	v_mov_b32_e32 v39, v8
	s_waitcnt vmcnt(38)
	v_mov_b32_e32 v40, v8
	v_mov_b32_e32 v41, v8
	v_mov_b32_e32 v42, v8
	v_mov_b32_e32 v43, v8
	v_mov_b32_e32 v44, v8
	v_mov_b32_e32 v45, v8
	v_mov_b32_e32 v46, v8
	v_mov_b32_e32 v47, v8
	v_mov_b32_e32 v48, v8
	v_mov_b32_e32 v49, v8
	v_mov_b32_e32 v50, v8
	v_mov_b32_e32 v51, v8
	v_mov_b32_e32 v52, v8
	v_mov_b32_e32 v53, v8
	v_mov_b32_e32 v54, v8
	v_mov_b32_e32 v55, v8
	v_mov_b32_e32 v56, v8
	v_mov_b32_e32 v57, v8
	v_mov_b32_e32 v58, v8
	v_mov_b32_e32 v59, v8
	v_mov_b32_e32 v60, v8
	v_mov_b32_e32 v61, v8
	v_mov_b32_e32 v62, v8
	v_mov_b32_e32 v63, v8
	v_mov_b32_e32 v64, v8
	v_mov_b32_e32 v65, v8
	v_mov_b32_e32 v66, v8
	v_mov_b32_e32 v67, v8
	v_mov_b32_e32 v68, v8
	v_mov_b32_e32 v69, v8
	v_mov_b32_e32 v70, v8
	v_mov_b32_e32 v71, v8
	v_mov_b32_e32 v72, v8
	v_mov_b32_e32 v73, v8
	v_mov_b32_e32 v74, v8
	v_mov_b32_e32 v75, v8
	v_mov_b32_e32 v76, v8
	v_mov_b32_e32 v77, v8
	v_mov_b32_e32 v78, v8
	v_mov_b32_e32 v79, v8
	v_mov_b32_e32 v80, v8
	v_mov_b32_e32 v81, v8
	v_mov_b32_e32 v82, v8
	v_mov_b32_e32 v83, v8
	v_mov_b32_e32 v84, v8
	v_mov_b32_e32 v85, v8
	v_mov_b32_e32 v86, v8
	v_mov_b32_e32 v87, v8
	s_waitcnt vmcnt(5)
	ds_write_b128 v94, v[0:3]
	s_waitcnt vmcnt(3)
	ds_write_b128 v94, v[4:7] offset:10240
	s_waitcnt vmcnt(2)
	ds_write_b128 v94, v[12:15] offset:20480
	s_waitcnt vmcnt(1)
	ds_write_b128 v94, v[16:19] offset:30720
	ds_write_b128 v94, v[24:27] offset:40960
	s_waitcnt vmcnt(0)
	ds_write_b128 v94, v[32:35] offset:51200
	s_waitcnt vmcnt(3)
	v_lshl_add_u64 v[12:13], v[88:89], 0, s[8:9]
	v_add_co_u32_e32 v0, vcc, 0x5770000, v12
	s_waitcnt vmcnt(1)
	v_lshl_add_u64 v[24:25], v[90:91], 0, s[8:9]
	v_addc_co_u32_e32 v1, vcc, 0, v13, vcc
	v_add_co_u32_e32 v4, vcc, 0x5790000, v12
	s_nop 1
	v_addc_co_u32_e32 v5, vcc, 0, v13, vcc
	v_add_co_u32_e32 v14, vcc, 0x57b0000, v12
	global_load_dwordx4 v[0:3], v[0:1], off offset:128
	s_nop 0
	global_load_dwordx4 v[4:7], v[4:5], off offset:128
	v_addc_co_u32_e32 v15, vcc, 0, v13, vcc
	v_add_co_u32_e32 v16, vcc, 0x57d0000, v12
	s_nop 1
	v_addc_co_u32_e32 v17, vcc, 0, v13, vcc
	v_add_co_u32_e32 v26, vcc, 0x2538000, v24
	global_load_dwordx4 v[12:15], v[14:15], off offset:128
	s_nop 0
	global_load_dwordx4 v[16:19], v[16:17], off offset:128
	v_addc_co_u32_e32 v27, vcc, 0, v25, vcc
	s_waitcnt vmcnt(4)
	v_add_co_u32_e32 v32, vcc, 0x2558000, v24
	s_nop 1
	v_addc_co_u32_e32 v33, vcc, 0, v25, vcc
	global_load_dwordx4 v[24:27], v[26:27], off offset:128
	s_nop 0
	global_load_dwordx4 v[32:35], v[32:33], off offset:128
	s_waitcnt lgkmcnt(0)
	s_barrier
	s_branch .LBB0_1132
.LBB0_1131:
	s_add_u32 s8, s8, 0x80
	s_addc_u32 s9, s9, 0
	s_cmpk_ge_i32 s8, 0x780
	s_cbranch_scc1 .Lmy_t14g_skip_1131
	s_waitcnt vmcnt(3)
	v_lshl_add_u64 v[12:13], v[88:89], 0, s[8:9]
	v_add_co_u32_e32 v0, vcc, 0x5770000, v12
	s_waitcnt vmcnt(1)
	v_lshl_add_u64 v[24:25], v[90:91], 0, s[8:9]
	v_addc_co_u32_e32 v1, vcc, 0, v13, vcc
	v_add_co_u32_e32 v4, vcc, 0x5790000, v12
	s_nop 1
	v_addc_co_u32_e32 v5, vcc, 0, v13, vcc
	v_add_co_u32_e32 v14, vcc, 0x57b0000, v12
	global_load_dwordx4 v[0:3], v[0:1], off offset:128
	s_nop 0
	global_load_dwordx4 v[4:7], v[4:5], off offset:128
	v_addc_co_u32_e32 v15, vcc, 0, v13, vcc
	v_add_co_u32_e32 v16, vcc, 0x57d0000, v12
	s_nop 1
	v_addc_co_u32_e32 v17, vcc, 0, v13, vcc
	v_add_co_u32_e32 v26, vcc, 0x2538000, v24
	global_load_dwordx4 v[12:15], v[14:15], off offset:128
	s_nop 0
	global_load_dwordx4 v[16:19], v[16:17], off offset:128
	v_addc_co_u32_e32 v27, vcc, 0, v25, vcc
	s_waitcnt vmcnt(4)
	v_add_co_u32_e32 v32, vcc, 0x2558000, v24
	s_nop 1
	v_addc_co_u32_e32 v33, vcc, 0, v25, vcc
	global_load_dwordx4 v[24:27], v[26:27], off offset:128
	s_nop 0
	global_load_dwordx4 v[32:35], v[32:33], off offset:128

; __device__ __forceinline__ f32x4 mfma16(bf16x8 a, bf16x8 b, f32x4 c) { return __builtin_amdgcn_mfma_f32_16x16x32_bf16(a, b, c, 0, 0, 0); }
; template <int NT, bool LOWREG = false>
; __device__ __forceinline__ void gemm_mainloop(const bh* __restrict__ A, long lda, const bh* __restrict__ B, long ldb, int K,
;                                               char* lds, f32x4 (&acc)[4][NT]) {
;     ...
;     const char* sb = lds + (kt & 1) * STAGE;
;     const char* a_base = sb + (wr * 64 + fr) * LROW + fq * 16;
;     const char* b_base = sb + A_BYTES + (wc * (16 * NT) + fr) * LROW + fq * 16;
; #pragma unroll
;     for (int ks = 0; ks < 2; ++ks) {
;       if constexpr (LOWREG) {
;         bf16x8 bfr[NT];
; #pragma unroll
;         for (int n = 0; n < NT; ++n) bfr[n] = *reinterpret_cast<const bf16x8*>(b_base + n * 16 * LROW + ks * 64);
; #pragma unroll
;         for (int mp = 0; mp < 2; ++mp) {
;           bf16x8 af[2];
; #pragma unroll
;           for (int m = 0; m < 2; ++m) af[m] = *reinterpret_cast<const bf16x8*>(a_base + (mp * 2 + m) * 16 * LROW + ks * 64);
;           __builtin_amdgcn_s_setprio(1);
; #pragma unroll
;           for (int m = 0; m < 2; ++m)
; #pragma unroll
;             for (int n = 0; n < NT; ++n) acc[mp * 2 + m][n] = mfma16(af[m], bfr[n], acc[mp * 2 + m][n]);
;           __builtin_amdgcn_s_setprio(0);
;         }
;       } else {
;       bf16x8 af[4], bfr[NT];
; #pragma unroll
;       for (int m = 0; m < 4; ++m) af[m] = *reinterpret_cast<const bf16x8*>(a_base + m * 16 * LROW + ks * 64);
; #pragma unroll
;       for (int n = 0; n < NT; ++n) bfr[n] = *reinterpret_cast<const bf16x8*>(b_base + n * 16 * LROW + ks * 64);
;       __builtin_amdgcn_s_setprio(1);
; #pragma unroll
;       for (int m = 0; m < 4; ++m)
; #pragma unroll
;         for (int n = 0; n < NT; ++n) acc[m][n] = mfma16(af[m], bfr[n], acc[m][n]);
;       __builtin_amdgcn_s_setprio(0);
;       }
;     }
;     if (more) {
;       char* wb = lds + ((kt + 1) & 1) * STAGE;
; #pragma unroll
;       for (int i = 0; i < 4; ++i) *reinterpret_cast<bf16x8*>(wb + (srow + 64 * i) * LROW + scol * 2) = ra[i];
; #pragma unroll
;       for (int i = 0; i < NB; ++i) *reinterpret_cast<bf16x8*>(wb + A_BYTES + (srow + 64 * i) * LROW + scol * 2) = rb[i];
;     }
;     __syncthreads();
.LBB0_1132:
	s_cmp_lt_u32 s3, 15
	s_cselect_b64 s[10:11], -1, 0
	s_cmp_gt_u32 s3, 14
	s_cbranch_scc1 .LBB0_1134
.LBB0_1134:
	s_add_i32 s5, s3, 1
	s_bitcmp1_b32 s3, 0
	s_cselect_b32 s3, 0xf000, 0
	s_add_i32 s3, s3, 32
	v_add3_u32 v97, s3, v95, v93
	v_add3_u32 v130, s3, v96, v93
	ds_read_b128 v[98:101], v97
	ds_read_b128 v[102:105], v97 offset:2560
	ds_read_b128 v[106:109], v97 offset:5120
	ds_read_b128 v[110:113], v97 offset:7680
	ds_read_b128 v[114:117], v130 offset:40960
	ds_read_b128 v[118:121], v130 offset:43520
	ds_read_b128 v[122:125], v130 offset:46080
	ds_read_b128 v[126:129], v130 offset:48640
	s_setprio 1
	s_waitcnt lgkmcnt(3)
	v_mfma_f32_16x16x32_bf16 v[84:87], v[98:101], v[114:117], v[84:87]
	s_waitcnt lgkmcnt(2)
	v_mfma_f32_16x16x32_bf16 v[80:83], v[98:101], v[118:121], v[80:83]
	s_waitcnt lgkmcnt(1)
	v_mfma_f32_16x16x32_bf16 v[76:79], v[98:101], v[122:125], v[76:79]
	s_waitcnt lgkmcnt(0)
	v_mfma_f32_16x16x32_bf16 v[72:75], v[98:101], v[126:129], v[72:75]
	v_mfma_f32_16x16x32_bf16 v[68:71], v[102:105], v[114:117], v[68:71]
	v_mfma_f32_16x16x32_bf16 v[64:67], v[102:105], v[118:121], v[64:67]
	v_mfma_f32_16x16x32_bf16 v[60:63], v[102:105], v[122:125], v[60:63]
	v_mfma_f32_16x16x32_bf16 v[56:59], v[102:105], v[126:129], v[56:59]
	v_mfma_f32_16x16x32_bf16 v[52:55], v[106:109], v[114:117], v[52:55]
	v_mfma_f32_16x16x32_bf16 v[48:51], v[106:109], v[118:121], v[48:51]
	v_mfma_f32_16x16x32_bf16 v[44:47], v[106:109], v[122:125], v[44:47]
	v_mfma_f32_16x16x32_bf16 v[40:43], v[106:109], v[126:129], v[40:43]
	v_mfma_f32_16x16x32_bf16 v[36:39], v[110:113], v[114:117], v[36:39]
	v_mfma_f32_16x16x32_bf16 v[28:31], v[110:113], v[118:121], v[28:31]
	v_mfma_f32_16x16x32_bf16 v[20:23], v[110:113], v[122:125], v[20:23]
	v_mfma_f32_16x16x32_bf16 v[8:11], v[110:113], v[126:129], v[8:11]
	s_setprio 0
	ds_read_b128 v[98:101], v97 offset:64
	ds_read_b128 v[102:105], v97 offset:2624
	ds_read_b128 v[106:109], v97 offset:5184
	ds_read_b128 v[110:113], v97 offset:7744
	ds_read_b128 v[114:117], v130 offset:41024
	ds_read_b128 v[118:121], v130 offset:43584
	ds_read_b128 v[122:125], v130 offset:46144
	ds_read_b128 v[126:129], v130 offset:48704
	s_setprio 1
	s_waitcnt lgkmcnt(3)
	v_mfma_f32_16x16x32_bf16 v[84:87], v[98:101], v[114:117], v[84:87]
	s_waitcnt lgkmcnt(2)
	v_mfma_f32_16x16x32_bf16 v[80:83], v[98:101], v[118:121], v[80:83]
	s_waitcnt lgkmcnt(1)
	v_mfma_f32_16x16x32_bf16 v[76:79], v[98:101], v[122:125], v[76:79]
	s_waitcnt lgkmcnt(0)
	v_mfma_f32_16x16x32_bf16 v[72:75], v[98:101], v[126:129], v[72:75]
	v_mfma_f32_16x16x32_bf16 v[68:71], v[102:105], v[114:117], v[68:71]
	v_mfma_f32_16x16x32_bf16 v[64:67], v[102:105], v[118:121], v[64:67]
	v_mfma_f32_16x16x32_bf16 v[60:63], v[102:105], v[122:125], v[60:63]
	v_mfma_f32_16x16x32_bf16 v[56:59], v[102:105], v[126:129], v[56:59]
	v_mfma_f32_16x16x32_bf16 v[52:55], v[106:109], v[114:117], v[52:55]
	v_mfma_f32_16x16x32_bf16 v[48:51], v[106:109], v[118:121], v[48:51]
	v_mfma_f32_16x16x32_bf16 v[44:47], v[106:109], v[122:125], v[44:47]
	v_mfma_f32_16x16x32_bf16 v[40:43], v[106:109], v[126:129], v[40:43]
	v_mfma_f32_16x16x32_bf16 v[36:39], v[110:113], v[114:117], v[36:39]
	v_mfma_f32_16x16x32_bf16 v[28:31], v[110:113], v[118:121], v[28:31]
	v_mfma_f32_16x16x32_bf16 v[20:23], v[110:113], v[122:125], v[20:23]
	v_mfma_f32_16x16x32_bf16 v[8:11], v[110:113], v[126:129], v[8:11]
	s_setprio 0
	s_andn2_b64 vcc, exec, s[10:11]
	s_cbranch_vccnz .LBB0_1131
	s_bitcmp1_b32 s5, 0
	s_cselect_b32 s3, 0xf000, 0
	v_add_u32_e32 v97, s3, v94
	s_waitcnt vmcnt(5)
	ds_write_b128 v97, v[0:3]
	s_waitcnt vmcnt(4)
	ds_write_b128 v97, v[4:7] offset:10240
	s_waitcnt vmcnt(3)
	ds_write_b128 v97, v[12:15] offset:20480
	s_waitcnt vmcnt(2)
	ds_write_b128 v97, v[16:19] offset:30720
	s_waitcnt vmcnt(1)
	ds_write_b128 v97, v[24:27] offset:40960
	s_waitcnt vmcnt(0)
	ds_write_b128 v97, v[32:35] offset:51200
	s_branch .LBB0_1131
